# MFMA order within each 32-MFMA block: same accumulator back-to-back (k0 then k1), no operand sharing between neighbours; plus s_sleep 2 stagger and saddr DMA
# speedup vs baseline: 1.0065x; 1.0063x over previous
.LBB0_147:
	s_sleep 2
	s_add_u32 s42, s40, 0xfff80080
	s_addc_u32 s43, s41, -1
	s_add_i32 s71, 0, 0x10000
	s_cmp_eq_u32 s63, 28
	s_cselect_b32 s45, s2, s43
	s_cselect_b32 s44, s5, s42
	s_cselect_b32 s43, s23, s62
	s_cselect_b32 s42, s25, s31
	s_add_i32 s73, 0, 0x14000
	s_waitcnt lgkmcnt(0)
	v_add_u32_e32 v156, s71, v169
	v_add_u32_e32 v178, s73, v169
	ds_read_b128 v[132:135], v156
	ds_read_b128 v[136:139], v156 offset:1024
	ds_read_b128 v[152:155], v156 offset:2048
	ds_read_b128 v[156:159], v156 offset:3072
	ds_read_b128 v[160:163], v178
	ds_read_b128 v[164:167], v178 offset:1024
	ds_read_b128 v[174:177], v178 offset:2048
	ds_read_b128 v[178:181], v178 offset:3072
	v_lshl_add_u64 v[202:203], s[40:41], 0, v[148:149]
	s_add_i32 m0, s53, 0xc000
	ds_read_b128 v[182:185], v171
	ds_read_b128 v[186:189], v171 offset:1024
	ds_read_b128 v[190:193], v171 offset:2048
	ds_read_b128 v[194:197], v171 offset:3072
	ds_read_b128 v[198:201], v171 offset:4096
	ds_read_b128 v[208:211], v171 offset:5120
	ds_read_b128 v[212:215], v171 offset:6144
	ds_read_b128 v[216:219], v171 offset:7168
	global_load_lds_dwordx4 v[202:203], off
	v_lshl_add_u64 v[202:203], s[40:41], 0, v[150:151]
	s_add_i32 m0, s53, 0xe000
	s_nop 0
	global_load_lds_dwordx4 v[202:203], off
	s_waitcnt vmcnt(8)
	s_waitcnt lgkmcnt(0)
	s_barrier
	s_setprio 1
	s_waitcnt lgkmcnt(0)
	v_mfma_f32_16x16x32_bf16 v[128:131], v[132:135], v[182:185], v[128:131]
	v_mfma_f32_16x16x32_bf16 v[128:131], v[136:139], v[186:189], v[128:131]
	v_mfma_f32_16x16x32_bf16 v[124:127], v[152:155], v[182:185], v[124:127]
	v_mfma_f32_16x16x32_bf16 v[124:127], v[156:159], v[186:189], v[124:127]
	v_mfma_f32_16x16x32_bf16 v[120:123], v[132:135], v[190:193], v[120:123]
	v_mfma_f32_16x16x32_bf16 v[120:123], v[136:139], v[194:197], v[120:123]
	v_mfma_f32_16x16x32_bf16 v[112:115], v[152:155], v[190:193], v[112:115]
	v_mfma_f32_16x16x32_bf16 v[112:115], v[156:159], v[194:197], v[112:115]
	v_mfma_f32_16x16x32_bf16 v[104:107], v[132:135], v[198:201], v[104:107]
	v_mfma_f32_16x16x32_bf16 v[104:107], v[136:139], v[208:211], v[104:107]
	v_mfma_f32_16x16x32_bf16 v[96:99], v[152:155], v[198:201], v[96:99]
	v_mfma_f32_16x16x32_bf16 v[96:99], v[156:159], v[208:211], v[96:99]
	v_mfma_f32_16x16x32_bf16 v[88:91], v[132:135], v[212:215], v[88:91]
	v_mfma_f32_16x16x32_bf16 v[88:91], v[136:139], v[216:219], v[88:91]
	v_mfma_f32_16x16x32_bf16 v[80:83], v[152:155], v[212:215], v[80:83]
	v_mfma_f32_16x16x32_bf16 v[80:83], v[156:159], v[216:219], v[80:83]
	v_mfma_f32_16x16x32_bf16 v[116:119], v[160:163], v[182:185], v[116:119]
	v_mfma_f32_16x16x32_bf16 v[116:119], v[164:167], v[186:189], v[116:119]
	v_mfma_f32_16x16x32_bf16 v[108:111], v[174:177], v[182:185], v[108:111]
	v_mfma_f32_16x16x32_bf16 v[108:111], v[178:181], v[186:189], v[108:111]
	v_mfma_f32_16x16x32_bf16 v[100:103], v[160:163], v[190:193], v[100:103]
	v_mfma_f32_16x16x32_bf16 v[100:103], v[164:167], v[194:197], v[100:103]
	v_mfma_f32_16x16x32_bf16 v[92:95], v[174:177], v[190:193], v[92:95]
	v_mfma_f32_16x16x32_bf16 v[92:95], v[178:181], v[194:197], v[92:95]
	v_mfma_f32_16x16x32_bf16 v[84:87], v[160:163], v[198:201], v[84:87]
	v_mfma_f32_16x16x32_bf16 v[84:87], v[164:167], v[208:211], v[84:87]
	v_mfma_f32_16x16x32_bf16 v[76:79], v[174:177], v[198:201], v[76:79]
	v_mfma_f32_16x16x32_bf16 v[76:79], v[178:181], v[208:211], v[76:79]
	v_mfma_f32_16x16x32_bf16 v[72:75], v[160:163], v[212:215], v[72:75]
	v_mfma_f32_16x16x32_bf16 v[72:75], v[164:167], v[216:219], v[72:75]
	v_mfma_f32_16x16x32_bf16 v[68:71], v[174:177], v[212:215], v[68:71]
	v_mfma_f32_16x16x32_bf16 v[68:71], v[178:181], v[216:219], v[68:71]
	s_setprio 0
	s_barrier
	s_sleep 2
	s_add_i32 s71, s71, s51
	v_lshl_add_u64 v[202:203], s[42:43], 0, v[2:3]
	s_mov_b32 m0, s71
	ds_read_b128 v[182:185], v171 offset:16384
	ds_read_b128 v[186:189], v171 offset:17408
	ds_read_b128 v[190:193], v171 offset:18432
	ds_read_b128 v[194:197], v171 offset:19456
	ds_read_b128 v[198:201], v171 offset:20480
	ds_read_b128 v[208:211], v171 offset:21504
	ds_read_b128 v[212:215], v171 offset:22528
	ds_read_b128 v[216:219], v171 offset:23552
	global_load_lds_dwordx4 v[202:203], off
	s_add_i32 m0, s71, 0x2000
	s_add_u32 s74, s42, 0x80000
	v_lshl_add_u64 v[204:205], s[42:43], 0, v[142:143]
	s_addc_u32 s75, s43, 0
	s_add_i32 s71, s73, s51
	global_load_lds_dwordx4 v[204:205], off
	v_lshl_add_u64 v[206:207], s[74:75], 0, v[2:3]
	s_mov_b32 m0, s71
	v_lshl_add_u64 v[220:221], s[44:45], 0, v[140:141]
	global_load_lds_dwordx4 v[206:207], off
	v_lshl_add_u64 v[206:207], s[74:75], 0, v[142:143]
	s_add_i32 m0, s71, 0x2000
	s_nop 0
	global_load_lds_dwordx4 v[206:207], off
	v_lshl_add_u64 v[206:207], s[44:45], 0, v[0:1]
	s_mov_b32 m0, s53
	s_nop 0
	global_load_lds_dwordx4 v[206:207], off
	s_mov_b32 m0, s54
	s_nop 0
	global_load_lds_dwordx4 v[220:221], off
	s_waitcnt vmcnt(8)
	s_waitcnt lgkmcnt(0)
	s_barrier
	s_setprio 1
	s_waitcnt lgkmcnt(0)
	v_mfma_f32_16x16x32_bf16 v[64:67], v[132:135], v[182:185], v[64:67]
	v_mfma_f32_16x16x32_bf16 v[64:67], v[136:139], v[186:189], v[64:67]
	v_mfma_f32_16x16x32_bf16 v[60:63], v[152:155], v[182:185], v[60:63]
	v_mfma_f32_16x16x32_bf16 v[60:63], v[156:159], v[186:189], v[60:63]
	v_mfma_f32_16x16x32_bf16 v[56:59], v[132:135], v[190:193], v[56:59]
	v_mfma_f32_16x16x32_bf16 v[56:59], v[136:139], v[194:197], v[56:59]
	v_mfma_f32_16x16x32_bf16 v[48:51], v[152:155], v[190:193], v[48:51]
	v_mfma_f32_16x16x32_bf16 v[48:51], v[156:159], v[194:197], v[48:51]
	v_mfma_f32_16x16x32_bf16 v[40:43], v[132:135], v[198:201], v[40:43]
	v_mfma_f32_16x16x32_bf16 v[40:43], v[136:139], v[208:211], v[40:43]
	v_mfma_f32_16x16x32_bf16 v[32:35], v[152:155], v[198:201], v[32:35]
	v_mfma_f32_16x16x32_bf16 v[32:35], v[156:159], v[208:211], v[32:35]
	v_mfma_f32_16x16x32_bf16 v[24:27], v[132:135], v[212:215], v[24:27]
	v_mfma_f32_16x16x32_bf16 v[24:27], v[136:139], v[216:219], v[24:27]
	v_mfma_f32_16x16x32_bf16 v[16:19], v[152:155], v[212:215], v[16:19]
	v_mfma_f32_16x16x32_bf16 v[16:19], v[156:159], v[216:219], v[16:19]
	v_mfma_f32_16x16x32_bf16 v[52:55], v[160:163], v[182:185], v[52:55]
	v_mfma_f32_16x16x32_bf16 v[52:55], v[164:167], v[186:189], v[52:55]
	v_mfma_f32_16x16x32_bf16 v[44:47], v[174:177], v[182:185], v[44:47]
	v_mfma_f32_16x16x32_bf16 v[44:47], v[178:181], v[186:189], v[44:47]
	v_mfma_f32_16x16x32_bf16 v[36:39], v[160:163], v[190:193], v[36:39]
	v_mfma_f32_16x16x32_bf16 v[36:39], v[164:167], v[194:197], v[36:39]
	v_mfma_f32_16x16x32_bf16 v[28:31], v[174:177], v[190:193], v[28:31]
	v_mfma_f32_16x16x32_bf16 v[28:31], v[178:181], v[194:197], v[28:31]
	v_mfma_f32_16x16x32_bf16 v[20:23], v[160:163], v[198:201], v[20:23]
	v_mfma_f32_16x16x32_bf16 v[20:23], v[164:167], v[208:211], v[20:23]
	v_mfma_f32_16x16x32_bf16 v[12:15], v[174:177], v[198:201], v[12:15]
	v_mfma_f32_16x16x32_bf16 v[12:15], v[178:181], v[208:211], v[12:15]
	v_mfma_f32_16x16x32_bf16 v[8:11], v[160:163], v[212:215], v[8:11]
	v_mfma_f32_16x16x32_bf16 v[8:11], v[164:167], v[216:219], v[8:11]
	v_mfma_f32_16x16x32_bf16 v[4:7], v[174:177], v[212:215], v[4:7]
	v_mfma_f32_16x16x32_bf16 v[4:7], v[178:181], v[216:219], v[4:7]
	s_setprio 0
	s_barrier
	s_sleep 2
	s_add_i32 s71, 0, 0x18000
	s_add_i32 s73, 0, 0x1c000
	v_add_u32_e32 v156, s71, v169
	v_add_u32_e32 v178, s73, v169
	ds_read_b128 v[132:135], v156
	ds_read_b128 v[136:139], v156 offset:1024
	ds_read_b128 v[152:155], v156 offset:2048
	ds_read_b128 v[156:159], v156 offset:3072
	ds_read_b128 v[160:163], v178
	ds_read_b128 v[164:167], v178 offset:1024
	ds_read_b128 v[174:177], v178 offset:2048
	ds_read_b128 v[178:181], v178 offset:3072
	s_add_u32 s44, s44, 0x80000
	s_addc_u32 s45, s45, 0
	s_mov_b32 m0, s55
	v_lshl_add_u64 v[222:223], s[44:45], 0, v[0:1]
	ds_read_b128 v[182:185], v171 offset:32768
	ds_read_b128 v[186:189], v171 offset:33792
	ds_read_b128 v[190:193], v171 offset:34816
	ds_read_b128 v[194:197], v171 offset:35840
	ds_read_b128 v[198:201], v171 offset:36864
	ds_read_b128 v[208:211], v171 offset:37888
	ds_read_b128 v[212:215], v171 offset:38912
	ds_read_b128 v[216:219], v171 offset:39936
	global_load_lds_dwordx4 v[222:223], off
	v_lshl_add_u64 v[222:223], s[44:45], 0, v[140:141]
	s_mov_b32 m0, s56
	s_nop 0
	global_load_lds_dwordx4 v[222:223], off
	s_waitcnt vmcnt(8)
	s_waitcnt lgkmcnt(0)
	s_barrier
	s_setprio 1
	s_waitcnt lgkmcnt(0)
	v_mfma_f32_16x16x32_bf16 v[128:131], v[132:135], v[182:185], v[128:131]
	v_mfma_f32_16x16x32_bf16 v[128:131], v[136:139], v[186:189], v[128:131]
	v_mfma_f32_16x16x32_bf16 v[124:127], v[152:155], v[182:185], v[124:127]
	v_mfma_f32_16x16x32_bf16 v[124:127], v[156:159], v[186:189], v[124:127]
	v_mfma_f32_16x16x32_bf16 v[120:123], v[132:135], v[190:193], v[120:123]
	v_mfma_f32_16x16x32_bf16 v[120:123], v[136:139], v[194:197], v[120:123]
	v_mfma_f32_16x16x32_bf16 v[112:115], v[152:155], v[190:193], v[112:115]
	v_mfma_f32_16x16x32_bf16 v[112:115], v[156:159], v[194:197], v[112:115]
	v_mfma_f32_16x16x32_bf16 v[104:107], v[132:135], v[198:201], v[104:107]
	v_mfma_f32_16x16x32_bf16 v[104:107], v[136:139], v[208:211], v[104:107]
	v_mfma_f32_16x16x32_bf16 v[96:99], v[152:155], v[198:201], v[96:99]
	v_mfma_f32_16x16x32_bf16 v[96:99], v[156:159], v[208:211], v[96:99]
	v_mfma_f32_16x16x32_bf16 v[88:91], v[132:135], v[212:215], v[88:91]
	v_mfma_f32_16x16x32_bf16 v[88:91], v[136:139], v[216:219], v[88:91]
	v_mfma_f32_16x16x32_bf16 v[80:83], v[152:155], v[212:215], v[80:83]
	v_mfma_f32_16x16x32_bf16 v[80:83], v[156:159], v[216:219], v[80:83]
	v_mfma_f32_16x16x32_bf16 v[116:119], v[160:163], v[182:185], v[116:119]
	v_mfma_f32_16x16x32_bf16 v[116:119], v[164:167], v[186:189], v[116:119]
	v_mfma_f32_16x16x32_bf16 v[108:111], v[174:177], v[182:185], v[108:111]
	v_mfma_f32_16x16x32_bf16 v[108:111], v[178:181], v[186:189], v[108:111]
	v_mfma_f32_16x16x32_bf16 v[100:103], v[160:163], v[190:193], v[100:103]
	v_mfma_f32_16x16x32_bf16 v[100:103], v[164:167], v[194:197], v[100:103]
	v_mfma_f32_16x16x32_bf16 v[92:95], v[174:177], v[190:193], v[92:95]
	v_mfma_f32_16x16x32_bf16 v[92:95], v[178:181], v[194:197], v[92:95]
	v_mfma_f32_16x16x32_bf16 v[84:87], v[160:163], v[198:201], v[84:87]
	v_mfma_f32_16x16x32_bf16 v[84:87], v[164:167], v[208:211], v[84:87]
	v_mfma_f32_16x16x32_bf16 v[76:79], v[174:177], v[198:201], v[76:79]
	v_mfma_f32_16x16x32_bf16 v[76:79], v[178:181], v[208:211], v[76:79]
	v_mfma_f32_16x16x32_bf16 v[72:75], v[160:163], v[212:215], v[72:75]
	v_mfma_f32_16x16x32_bf16 v[72:75], v[164:167], v[216:219], v[72:75]
	v_mfma_f32_16x16x32_bf16 v[68:71], v[174:177], v[212:215], v[68:71]
	v_mfma_f32_16x16x32_bf16 v[68:71], v[178:181], v[216:219], v[68:71]
	s_setprio 0
	s_barrier
	s_sleep 2
	s_add_i32 s44, s71, s51
	v_lshl_add_u64 v[202:203], v[202:203], 0, s[66:67]
	s_mov_b32 m0, s44
	ds_read_b128 v[182:185], v171 offset:49152
	ds_read_b128 v[186:189], v171 offset:50176
	ds_read_b128 v[190:193], v171 offset:51200
	ds_read_b128 v[194:197], v171 offset:52224
	ds_read_b128 v[198:201], v171 offset:53248
	ds_read_b128 v[208:211], v171 offset:54272
	ds_read_b128 v[212:215], v171 offset:55296
	ds_read_b128 v[216:219], v171 offset:56320
	global_load_lds_dwordx4 v[202:203], off
	s_add_i32 m0, s44, 0x2000
	s_add_u32 s42, s42, 0x80080
	v_lshl_add_u64 v[202:203], v[204:205], 0, s[66:67]
	s_addc_u32 s43, s43, 0
	s_add_i32 s44, s73, s51
	global_load_lds_dwordx4 v[202:203], off
	v_lshl_add_u64 v[202:203], s[42:43], 0, v[2:3]
	s_mov_b32 m0, s44
	s_nop 0
	global_load_lds_dwordx4 v[202:203], off
	v_lshl_add_u64 v[202:203], s[42:43], 0, v[142:143]
	s_add_i32 m0, s44, 0x2000
	s_nop 0
	global_load_lds_dwordx4 v[202:203], off
	v_lshl_add_u64 v[202:203], v[206:207], 0, s[66:67]
	s_mov_b32 m0, s65
	s_nop 0
	global_load_lds_dwordx4 v[202:203], off
	v_lshl_add_u64 v[202:203], v[220:221], 0, s[66:67]
	s_mov_b32 m0, s68
	s_nop 0
	global_load_lds_dwordx4 v[202:203], off
	s_waitcnt vmcnt(8)
	s_waitcnt lgkmcnt(0)
	s_barrier
	s_setprio 1
	s_waitcnt lgkmcnt(0)
	v_mfma_f32_16x16x32_bf16 v[64:67], v[132:135], v[182:185], v[64:67]
	v_mfma_f32_16x16x32_bf16 v[64:67], v[136:139], v[186:189], v[64:67]
	v_mfma_f32_16x16x32_bf16 v[60:63], v[152:155], v[182:185], v[60:63]
	v_mfma_f32_16x16x32_bf16 v[60:63], v[156:159], v[186:189], v[60:63]
	v_mfma_f32_16x16x32_bf16 v[56:59], v[132:135], v[190:193], v[56:59]
	v_mfma_f32_16x16x32_bf16 v[56:59], v[136:139], v[194:197], v[56:59]
	v_mfma_f32_16x16x32_bf16 v[48:51], v[152:155], v[190:193], v[48:51]
	v_mfma_f32_16x16x32_bf16 v[48:51], v[156:159], v[194:197], v[48:51]
	v_mfma_f32_16x16x32_bf16 v[40:43], v[132:135], v[198:201], v[40:43]
	v_mfma_f32_16x16x32_bf16 v[40:43], v[136:139], v[208:211], v[40:43]
	v_mfma_f32_16x16x32_bf16 v[32:35], v[152:155], v[198:201], v[32:35]
	v_mfma_f32_16x16x32_bf16 v[32:35], v[156:159], v[208:211], v[32:35]
	v_mfma_f32_16x16x32_bf16 v[24:27], v[132:135], v[212:215], v[24:27]
	v_mfma_f32_16x16x32_bf16 v[24:27], v[136:139], v[216:219], v[24:27]
	v_mfma_f32_16x16x32_bf16 v[16:19], v[152:155], v[212:215], v[16:19]
	v_mfma_f32_16x16x32_bf16 v[16:19], v[156:159], v[216:219], v[16:19]
	v_mfma_f32_16x16x32_bf16 v[52:55], v[160:163], v[182:185], v[52:55]
	v_mfma_f32_16x16x32_bf16 v[52:55], v[164:167], v[186:189], v[52:55]
	v_mfma_f32_16x16x32_bf16 v[44:47], v[174:177], v[182:185], v[44:47]
	v_mfma_f32_16x16x32_bf16 v[44:47], v[178:181], v[186:189], v[44:47]
	v_mfma_f32_16x16x32_bf16 v[36:39], v[160:163], v[190:193], v[36:39]
	v_mfma_f32_16x16x32_bf16 v[36:39], v[164:167], v[194:197], v[36:39]
	v_mfma_f32_16x16x32_bf16 v[28:31], v[174:177], v[190:193], v[28:31]
	v_mfma_f32_16x16x32_bf16 v[28:31], v[178:181], v[194:197], v[28:31]
	v_mfma_f32_16x16x32_bf16 v[20:23], v[160:163], v[198:201], v[20:23]
	v_mfma_f32_16x16x32_bf16 v[20:23], v[164:167], v[208:211], v[20:23]
	v_mfma_f32_16x16x32_bf16 v[12:15], v[174:177], v[198:201], v[12:15]
	v_mfma_f32_16x16x32_bf16 v[12:15], v[178:181], v[208:211], v[12:15]
	v_mfma_f32_16x16x32_bf16 v[8:11], v[160:163], v[212:215], v[8:11]
	v_mfma_f32_16x16x32_bf16 v[8:11], v[164:167], v[216:219], v[8:11]
	v_mfma_f32_16x16x32_bf16 v[4:7], v[174:177], v[212:215], v[4:7]
	v_mfma_f32_16x16x32_bf16 v[4:7], v[178:181], v[216:219], v[4:7]
	s_setprio 0
	s_barrier
	s_add_i32 s63, s63, 2
	s_add_u32 s40, s40, 0x100
	s_addc_u32 s41, s41, 0
	s_add_u32 s31, s31, 0x100
	s_addc_u32 s62, s62, 0
	s_cmp_gt_u32 s63, 29
	s_cbranch_scc0 .LBB0_147
	s_and_b64 vcc, exec, s[18:19]
	s_cbranch_vccz .LBB0_150
	s_barrier

.LBB0_211:
	s_sleep 2
	s_add_u32 s30, s28, 0xfff80080
	s_addc_u32 s31, s29, -1
	s_add_i32 s58, 0, 0x10000
	s_cmp_eq_u32 s57, 28
	s_cselect_b32 s39, s21, s31
	s_cselect_b32 s38, s53, s30
	v_add_u32_e32 v148, s58, v151
	s_cselect_b32 s31, s19, s56
	s_cselect_b32 s30, s54, s55
	s_add_i32 s60, 0, 0x14000
	ds_read_b128 v[140:143], v148
	ds_read_b128 v[144:147], v148 offset:1024
	ds_read_b128 v[156:159], v148 offset:2048
	ds_read_b128 v[160:163], v148 offset:3072
	v_add_u32_e32 v148, s60, v151
	ds_read_b128 v[164:167], v148
	ds_read_b128 v[168:171], v148 offset:1024
	ds_read_b128 v[172:175], v148 offset:2048
	ds_read_b128 v[176:179], v148 offset:3072
	s_add_i32 m0, s43, 0xc000
	ds_read_b128 v[180:183], v154
	ds_read_b128 v[184:187], v154 offset:1024
	ds_read_b128 v[188:191], v154 offset:2048
	ds_read_b128 v[192:195], v154 offset:3072
	ds_read_b128 v[196:199], v154 offset:4096
	ds_read_b128 v[200:203], v154 offset:5120
	ds_read_b128 v[208:211], v154 offset:6144
	ds_read_b128 v[212:215], v154 offset:7168
	global_load_lds_dwordx4 v136, s[28:29]
	s_add_i32 m0, s43, 0xe000
	s_nop 0
	global_load_lds_dwordx4 v138, s[28:29]
	s_waitcnt vmcnt(8)
	s_waitcnt lgkmcnt(0)
	s_barrier
	s_setprio 1
	s_waitcnt lgkmcnt(0)
	v_mfma_f32_16x16x32_bf16 v[128:131], v[140:143], v[180:183], v[128:131]
	v_mfma_f32_16x16x32_bf16 v[128:131], v[144:147], v[184:187], v[128:131]
	v_mfma_f32_16x16x32_bf16 v[124:127], v[156:159], v[180:183], v[124:127]
	v_mfma_f32_16x16x32_bf16 v[124:127], v[160:163], v[184:187], v[124:127]
	v_mfma_f32_16x16x32_bf16 v[112:115], v[140:143], v[188:191], v[112:115]
	v_mfma_f32_16x16x32_bf16 v[112:115], v[144:147], v[192:195], v[112:115]
	v_mfma_f32_16x16x32_bf16 v[108:111], v[156:159], v[188:191], v[108:111]
	v_mfma_f32_16x16x32_bf16 v[108:111], v[160:163], v[192:195], v[108:111]
	v_mfma_f32_16x16x32_bf16 v[96:99], v[140:143], v[196:199], v[96:99]
	v_mfma_f32_16x16x32_bf16 v[96:99], v[144:147], v[200:203], v[96:99]
	v_mfma_f32_16x16x32_bf16 v[92:95], v[156:159], v[196:199], v[92:95]
	v_mfma_f32_16x16x32_bf16 v[92:95], v[160:163], v[200:203], v[92:95]
	v_mfma_f32_16x16x32_bf16 v[80:83], v[140:143], v[208:211], v[80:83]
	v_mfma_f32_16x16x32_bf16 v[80:83], v[144:147], v[212:215], v[80:83]
	v_mfma_f32_16x16x32_bf16 v[76:79], v[156:159], v[208:211], v[76:79]
	v_mfma_f32_16x16x32_bf16 v[76:79], v[160:163], v[212:215], v[76:79]
	v_mfma_f32_16x16x32_bf16 v[120:123], v[164:167], v[180:183], v[120:123]
	v_mfma_f32_16x16x32_bf16 v[120:123], v[168:171], v[184:187], v[120:123]
	v_mfma_f32_16x16x32_bf16 v[116:119], v[172:175], v[180:183], v[116:119]
	v_mfma_f32_16x16x32_bf16 v[116:119], v[176:179], v[184:187], v[116:119]
	v_mfma_f32_16x16x32_bf16 v[104:107], v[164:167], v[188:191], v[104:107]
	v_mfma_f32_16x16x32_bf16 v[104:107], v[168:171], v[192:195], v[104:107]
	v_mfma_f32_16x16x32_bf16 v[100:103], v[172:175], v[188:191], v[100:103]
	v_mfma_f32_16x16x32_bf16 v[100:103], v[176:179], v[192:195], v[100:103]
	v_mfma_f32_16x16x32_bf16 v[88:91], v[164:167], v[196:199], v[88:91]
	v_mfma_f32_16x16x32_bf16 v[88:91], v[168:171], v[200:203], v[88:91]
	v_mfma_f32_16x16x32_bf16 v[84:87], v[172:175], v[196:199], v[84:87]
	v_mfma_f32_16x16x32_bf16 v[84:87], v[176:179], v[200:203], v[84:87]
	v_mfma_f32_16x16x32_bf16 v[72:75], v[164:167], v[208:211], v[72:75]
	v_mfma_f32_16x16x32_bf16 v[72:75], v[168:171], v[212:215], v[72:75]
	v_mfma_f32_16x16x32_bf16 v[68:71], v[172:175], v[208:211], v[68:71]
	v_mfma_f32_16x16x32_bf16 v[68:71], v[176:179], v[212:215], v[68:71]
	s_setprio 0
	s_barrier
	s_sleep 2
	s_add_i32 s58, s58, s41
	s_mov_b32 m0, s58
	ds_read_b128 v[180:183], v154 offset:16384
	ds_read_b128 v[184:187], v154 offset:17408
	ds_read_b128 v[188:191], v154 offset:18432
	ds_read_b128 v[192:195], v154 offset:19456
	ds_read_b128 v[196:199], v154 offset:20480
	ds_read_b128 v[200:203], v154 offset:21504
	ds_read_b128 v[208:211], v154 offset:22528
	ds_read_b128 v[212:215], v154 offset:23552
	global_load_lds_dwordx4 v2, s[30:31]
	s_add_i32 m0, s58, 0x2000
	s_add_u32 s62, s30, 0x80000
	s_addc_u32 s63, s31, 0
	s_add_i32 s58, s60, s41
	global_load_lds_dwordx4 v0, s[30:31]
	s_mov_b32 m0, s58
	s_nop 0
	global_load_lds_dwordx4 v2, s[62:63]
	s_add_i32 m0, s58, 0x2000
	s_nop 0
	global_load_lds_dwordx4 v0, s[62:63]
	s_mov_b32 m0, s43
	s_nop 0
	global_load_lds_dwordx4 v134, s[38:39]
	s_mov_b32 m0, s44
	s_nop 0
	global_load_lds_dwordx4 v132, s[38:39]
	s_waitcnt vmcnt(8)
	s_waitcnt lgkmcnt(0)
	s_barrier
	s_setprio 1
	s_waitcnt lgkmcnt(0)
	v_mfma_f32_16x16x32_bf16 v[64:67], v[140:143], v[180:183], v[64:67]
	v_mfma_f32_16x16x32_bf16 v[64:67], v[144:147], v[184:187], v[64:67]
	v_mfma_f32_16x16x32_bf16 v[60:63], v[156:159], v[180:183], v[60:63]
	v_mfma_f32_16x16x32_bf16 v[60:63], v[160:163], v[184:187], v[60:63]
	v_mfma_f32_16x16x32_bf16 v[48:51], v[140:143], v[188:191], v[48:51]
	v_mfma_f32_16x16x32_bf16 v[48:51], v[144:147], v[192:195], v[48:51]
	v_mfma_f32_16x16x32_bf16 v[44:47], v[156:159], v[188:191], v[44:47]
	v_mfma_f32_16x16x32_bf16 v[44:47], v[160:163], v[192:195], v[44:47]
	v_mfma_f32_16x16x32_bf16 v[32:35], v[140:143], v[196:199], v[32:35]
	v_mfma_f32_16x16x32_bf16 v[32:35], v[144:147], v[200:203], v[32:35]
	v_mfma_f32_16x16x32_bf16 v[28:31], v[156:159], v[196:199], v[28:31]
	v_mfma_f32_16x16x32_bf16 v[28:31], v[160:163], v[200:203], v[28:31]
	v_mfma_f32_16x16x32_bf16 v[16:19], v[140:143], v[208:211], v[16:19]
	v_mfma_f32_16x16x32_bf16 v[16:19], v[144:147], v[212:215], v[16:19]
	v_mfma_f32_16x16x32_bf16 v[12:15], v[156:159], v[208:211], v[12:15]
	v_mfma_f32_16x16x32_bf16 v[12:15], v[160:163], v[212:215], v[12:15]
	v_mfma_f32_16x16x32_bf16 v[56:59], v[164:167], v[180:183], v[56:59]
	v_mfma_f32_16x16x32_bf16 v[56:59], v[168:171], v[184:187], v[56:59]
	v_mfma_f32_16x16x32_bf16 v[52:55], v[172:175], v[180:183], v[52:55]
	v_mfma_f32_16x16x32_bf16 v[52:55], v[176:179], v[184:187], v[52:55]
	v_mfma_f32_16x16x32_bf16 v[40:43], v[164:167], v[188:191], v[40:43]
	v_mfma_f32_16x16x32_bf16 v[40:43], v[168:171], v[192:195], v[40:43]
	v_mfma_f32_16x16x32_bf16 v[36:39], v[172:175], v[188:191], v[36:39]
	v_mfma_f32_16x16x32_bf16 v[36:39], v[176:179], v[192:195], v[36:39]
	v_mfma_f32_16x16x32_bf16 v[24:27], v[164:167], v[196:199], v[24:27]
	v_mfma_f32_16x16x32_bf16 v[24:27], v[168:171], v[200:203], v[24:27]
	v_mfma_f32_16x16x32_bf16 v[20:23], v[172:175], v[196:199], v[20:23]
	v_mfma_f32_16x16x32_bf16 v[20:23], v[176:179], v[200:203], v[20:23]
	v_mfma_f32_16x16x32_bf16 v[8:11], v[164:167], v[208:211], v[8:11]
	v_mfma_f32_16x16x32_bf16 v[8:11], v[168:171], v[212:215], v[8:11]
	v_mfma_f32_16x16x32_bf16 v[4:7], v[172:175], v[208:211], v[4:7]
	v_mfma_f32_16x16x32_bf16 v[4:7], v[176:179], v[212:215], v[4:7]
	s_setprio 0
	s_barrier
	s_sleep 2
	s_add_i32 s58, 0, 0x18000
	v_add_u32_e32 v155, s58, v151
	s_add_i32 s60, 0, 0x1c000
	ds_read_b128 v[140:143], v155
	ds_read_b128 v[144:147], v155 offset:1024
	ds_read_b128 v[156:159], v155 offset:2048
	ds_read_b128 v[160:163], v155 offset:3072
	v_add_u32_e32 v155, s60, v151
	ds_read_b128 v[164:167], v155
	ds_read_b128 v[168:171], v155 offset:1024
	ds_read_b128 v[172:175], v155 offset:2048
	ds_read_b128 v[176:179], v155 offset:3072
	s_add_u32 s38, s38, 0x80000
	s_addc_u32 s39, s39, 0
	s_mov_b32 m0, s45
	ds_read_b128 v[180:183], v154 offset:32768
	ds_read_b128 v[184:187], v154 offset:33792
	ds_read_b128 v[188:191], v154 offset:34816
	ds_read_b128 v[192:195], v154 offset:35840
	ds_read_b128 v[196:199], v154 offset:36864
	ds_read_b128 v[200:203], v154 offset:37888
	ds_read_b128 v[208:211], v154 offset:38912
	ds_read_b128 v[212:215], v154 offset:39936
	global_load_lds_dwordx4 v134, s[38:39]
	s_mov_b32 m0, s47
	s_nop 0
	global_load_lds_dwordx4 v132, s[38:39]
	s_waitcnt vmcnt(8)
	s_waitcnt lgkmcnt(0)
	s_barrier
	s_setprio 1
	s_waitcnt lgkmcnt(0)
	v_mfma_f32_16x16x32_bf16 v[128:131], v[140:143], v[180:183], v[128:131]
	v_mfma_f32_16x16x32_bf16 v[128:131], v[144:147], v[184:187], v[128:131]
	v_mfma_f32_16x16x32_bf16 v[124:127], v[156:159], v[180:183], v[124:127]
	v_mfma_f32_16x16x32_bf16 v[124:127], v[160:163], v[184:187], v[124:127]
	v_mfma_f32_16x16x32_bf16 v[112:115], v[140:143], v[188:191], v[112:115]
	v_mfma_f32_16x16x32_bf16 v[112:115], v[144:147], v[192:195], v[112:115]
	v_mfma_f32_16x16x32_bf16 v[108:111], v[156:159], v[188:191], v[108:111]
	v_mfma_f32_16x16x32_bf16 v[108:111], v[160:163], v[192:195], v[108:111]
	v_mfma_f32_16x16x32_bf16 v[96:99], v[140:143], v[196:199], v[96:99]
	v_mfma_f32_16x16x32_bf16 v[96:99], v[144:147], v[200:203], v[96:99]
	v_mfma_f32_16x16x32_bf16 v[92:95], v[156:159], v[196:199], v[92:95]
	v_mfma_f32_16x16x32_bf16 v[92:95], v[160:163], v[200:203], v[92:95]
	v_mfma_f32_16x16x32_bf16 v[80:83], v[140:143], v[208:211], v[80:83]
	v_mfma_f32_16x16x32_bf16 v[80:83], v[144:147], v[212:215], v[80:83]
	v_mfma_f32_16x16x32_bf16 v[76:79], v[156:159], v[208:211], v[76:79]
	v_mfma_f32_16x16x32_bf16 v[76:79], v[160:163], v[212:215], v[76:79]
	v_mfma_f32_16x16x32_bf16 v[120:123], v[164:167], v[180:183], v[120:123]
	v_mfma_f32_16x16x32_bf16 v[120:123], v[168:171], v[184:187], v[120:123]
	v_mfma_f32_16x16x32_bf16 v[116:119], v[172:175], v[180:183], v[116:119]
	v_mfma_f32_16x16x32_bf16 v[116:119], v[176:179], v[184:187], v[116:119]
	v_mfma_f32_16x16x32_bf16 v[104:107], v[164:167], v[188:191], v[104:107]
	v_mfma_f32_16x16x32_bf16 v[104:107], v[168:171], v[192:195], v[104:107]
	v_mfma_f32_16x16x32_bf16 v[100:103], v[172:175], v[188:191], v[100:103]
	v_mfma_f32_16x16x32_bf16 v[100:103], v[176:179], v[192:195], v[100:103]
	v_mfma_f32_16x16x32_bf16 v[88:91], v[164:167], v[196:199], v[88:91]
	v_mfma_f32_16x16x32_bf16 v[88:91], v[168:171], v[200:203], v[88:91]
	v_mfma_f32_16x16x32_bf16 v[84:87], v[172:175], v[196:199], v[84:87]
	v_mfma_f32_16x16x32_bf16 v[84:87], v[176:179], v[200:203], v[84:87]
	v_mfma_f32_16x16x32_bf16 v[72:75], v[164:167], v[208:211], v[72:75]
	v_mfma_f32_16x16x32_bf16 v[72:75], v[168:171], v[212:215], v[72:75]
	v_mfma_f32_16x16x32_bf16 v[68:71], v[172:175], v[208:211], v[68:71]
	v_mfma_f32_16x16x32_bf16 v[68:71], v[176:179], v[212:215], v[68:71]
	s_setprio 0
	s_barrier
	s_sleep 2
	s_add_i32 s62, s58, s41
	s_add_u32 s30, s30, 0x80
	s_addc_u32 s31, s31, 0
	s_mov_b32 m0, s62
	ds_read_b128 v[180:183], v154 offset:49152
	ds_read_b128 v[184:187], v154 offset:50176
	ds_read_b128 v[188:191], v154 offset:51200
	ds_read_b128 v[192:195], v154 offset:52224
	ds_read_b128 v[196:199], v154 offset:53248
	ds_read_b128 v[200:203], v154 offset:54272
	ds_read_b128 v[208:211], v154 offset:55296
	ds_read_b128 v[212:215], v154 offset:56320
	global_load_lds_dwordx4 v2, s[30:31]
	s_add_i32 m0, s62, 0x2000
	s_nop 0
	s_add_i32 s62, s60, s41
	global_load_lds_dwordx4 v0, s[30:31]
	s_add_u32 s30, s30, 0x80000
	s_addc_u32 s31, s31, 0
	s_mov_b32 m0, s62
	s_nop 0
	global_load_lds_dwordx4 v2, s[30:31]
	s_add_i32 m0, s62, 0x2000
	s_nop 0
	global_load_lds_dwordx4 v0, s[30:31]
	s_sub_u32 s38, s38, 0x7ff80
	s_subb_u32 s39, s39, 0
	s_mov_b32 m0, s48
	s_nop 0
	global_load_lds_dwordx4 v134, s[38:39]
	s_mov_b32 m0, s49
	s_nop 0
	global_load_lds_dwordx4 v132, s[38:39]
	s_waitcnt vmcnt(8)
	s_waitcnt lgkmcnt(0)
	s_barrier
	s_setprio 1
	s_waitcnt lgkmcnt(0)
	v_mfma_f32_16x16x32_bf16 v[64:67], v[140:143], v[180:183], v[64:67]
	v_mfma_f32_16x16x32_bf16 v[64:67], v[144:147], v[184:187], v[64:67]
	v_mfma_f32_16x16x32_bf16 v[60:63], v[156:159], v[180:183], v[60:63]
	v_mfma_f32_16x16x32_bf16 v[60:63], v[160:163], v[184:187], v[60:63]
	v_mfma_f32_16x16x32_bf16 v[48:51], v[140:143], v[188:191], v[48:51]
	v_mfma_f32_16x16x32_bf16 v[48:51], v[144:147], v[192:195], v[48:51]
	v_mfma_f32_16x16x32_bf16 v[44:47], v[156:159], v[188:191], v[44:47]
	v_mfma_f32_16x16x32_bf16 v[44:47], v[160:163], v[192:195], v[44:47]
	v_mfma_f32_16x16x32_bf16 v[32:35], v[140:143], v[196:199], v[32:35]
	v_mfma_f32_16x16x32_bf16 v[32:35], v[144:147], v[200:203], v[32:35]
	v_mfma_f32_16x16x32_bf16 v[28:31], v[156:159], v[196:199], v[28:31]
	v_mfma_f32_16x16x32_bf16 v[28:31], v[160:163], v[200:203], v[28:31]
	v_mfma_f32_16x16x32_bf16 v[16:19], v[140:143], v[208:211], v[16:19]
	v_mfma_f32_16x16x32_bf16 v[16:19], v[144:147], v[212:215], v[16:19]
	v_mfma_f32_16x16x32_bf16 v[12:15], v[156:159], v[208:211], v[12:15]
	v_mfma_f32_16x16x32_bf16 v[12:15], v[160:163], v[212:215], v[12:15]
	v_mfma_f32_16x16x32_bf16 v[56:59], v[164:167], v[180:183], v[56:59]
	v_mfma_f32_16x16x32_bf16 v[56:59], v[168:171], v[184:187], v[56:59]
	v_mfma_f32_16x16x32_bf16 v[52:55], v[172:175], v[180:183], v[52:55]
	v_mfma_f32_16x16x32_bf16 v[52:55], v[176:179], v[184:187], v[52:55]
	v_mfma_f32_16x16x32_bf16 v[40:43], v[164:167], v[188:191], v[40:43]
	v_mfma_f32_16x16x32_bf16 v[40:43], v[168:171], v[192:195], v[40:43]
	v_mfma_f32_16x16x32_bf16 v[36:39], v[172:175], v[188:191], v[36:39]
	v_mfma_f32_16x16x32_bf16 v[36:39], v[176:179], v[192:195], v[36:39]
	v_mfma_f32_16x16x32_bf16 v[24:27], v[164:167], v[196:199], v[24:27]
	v_mfma_f32_16x16x32_bf16 v[24:27], v[168:171], v[200:203], v[24:27]
	v_mfma_f32_16x16x32_bf16 v[20:23], v[172:175], v[196:199], v[20:23]
	v_mfma_f32_16x16x32_bf16 v[20:23], v[176:179], v[200:203], v[20:23]
	v_mfma_f32_16x16x32_bf16 v[8:11], v[164:167], v[208:211], v[8:11]
	v_mfma_f32_16x16x32_bf16 v[8:11], v[168:171], v[212:215], v[8:11]
	v_mfma_f32_16x16x32_bf16 v[4:7], v[172:175], v[208:211], v[4:7]
	v_mfma_f32_16x16x32_bf16 v[4:7], v[176:179], v[212:215], v[4:7]
	s_setprio 0
	s_barrier
	s_add_i32 s57, s57, 2
	s_add_u32 s28, s28, 0x100
	s_addc_u32 s29, s29, 0
	s_add_u32 s55, s55, 0x100
	s_addc_u32 s56, s56, 0
	s_cmp_gt_u32 s57, 29
	s_cbranch_scc0 .LBB0_211
	s_and_b64 vcc, exec, s[16:17]
	s_cbranch_vccz .LBB0_214
	s_barrier

.LBB0_301:
	s_sleep 2
	s_add_u32 s18, s16, 0x100
	s_addc_u32 s19, s17, 0
	s_add_i32 s49, 0, 0x10000
	s_cmpk_eq_i32 s48, 0x54
	s_cselect_b32 s23, s13, s19
	s_cselect_b32 s22, s12, s18
	s_cselect_b32 s21, s15, s41
	s_cselect_b32 s20, s14, s40
	s_add_i32 s50, 0, 0x14000
	v_add_u32_e32 v144, s49, v219
	v_add_u32_e32 v160, s50, v219
	ds_read_b128 v[124:127], v144
	ds_read_b128 v[128:131], v144 offset:1024
	ds_read_b128 v[140:143], v144 offset:2048
	ds_read_b128 v[144:147], v144 offset:3072
	ds_read_b128 v[148:151], v160
	ds_read_b128 v[152:155], v160 offset:1024
	ds_read_b128 v[156:159], v160 offset:2048
	ds_read_b128 v[160:163], v160 offset:3072
	v_lshl_add_u64 v[204:205], s[16:17], 0, v[192:193]
	s_add_i32 m0, s28, 0xc000
	ds_read_b128 v[164:167], v221
	ds_read_b128 v[168:171], v221 offset:1024
	ds_read_b128 v[172:175], v221 offset:2048
	ds_read_b128 v[176:179], v221 offset:3072
	ds_read_b128 v[180:183], v221 offset:4096
	ds_read_b128 v[184:187], v221 offset:5120
	ds_read_b128 v[196:199], v221 offset:6144
	ds_read_b128 v[200:203], v221 offset:7168
	global_load_lds_dwordx4 v[204:205], off
	v_lshl_add_u64 v[204:205], s[16:17], 0, v[194:195]
	s_add_i32 m0, s28, 0xe000
	s_nop 0
	global_load_lds_dwordx4 v[204:205], off
	s_waitcnt vmcnt(8)
	s_waitcnt lgkmcnt(0)
	s_barrier
	s_setprio 1
	s_waitcnt lgkmcnt(0)
	v_mfma_f32_16x16x32_bf16 v[136:139], v[124:127], v[164:167], v[136:139]
	v_mfma_f32_16x16x32_bf16 v[136:139], v[128:131], v[168:171], v[136:139]
	v_mfma_f32_16x16x32_bf16 v[132:135], v[140:143], v[164:167], v[132:135]
	v_mfma_f32_16x16x32_bf16 v[132:135], v[144:147], v[168:171], v[132:135]
	v_mfma_f32_16x16x32_bf16 v[112:115], v[124:127], v[172:175], v[112:115]
	v_mfma_f32_16x16x32_bf16 v[112:115], v[128:131], v[176:179], v[112:115]
	v_mfma_f32_16x16x32_bf16 v[108:111], v[140:143], v[172:175], v[108:111]
	v_mfma_f32_16x16x32_bf16 v[108:111], v[144:147], v[176:179], v[108:111]
	v_mfma_f32_16x16x32_bf16 v[96:99], v[124:127], v[180:183], v[96:99]
	v_mfma_f32_16x16x32_bf16 v[96:99], v[128:131], v[184:187], v[96:99]
	v_mfma_f32_16x16x32_bf16 v[92:95], v[140:143], v[180:183], v[92:95]
	v_mfma_f32_16x16x32_bf16 v[92:95], v[144:147], v[184:187], v[92:95]
	v_mfma_f32_16x16x32_bf16 v[80:83], v[124:127], v[196:199], v[80:83]
	v_mfma_f32_16x16x32_bf16 v[80:83], v[128:131], v[200:203], v[80:83]
	v_mfma_f32_16x16x32_bf16 v[76:79], v[140:143], v[196:199], v[76:79]
	v_mfma_f32_16x16x32_bf16 v[76:79], v[144:147], v[200:203], v[76:79]
	v_mfma_f32_16x16x32_bf16 v[120:123], v[148:151], v[164:167], v[120:123]
	v_mfma_f32_16x16x32_bf16 v[120:123], v[152:155], v[168:171], v[120:123]
	v_mfma_f32_16x16x32_bf16 v[116:119], v[156:159], v[164:167], v[116:119]
	v_mfma_f32_16x16x32_bf16 v[116:119], v[160:163], v[168:171], v[116:119]
	v_mfma_f32_16x16x32_bf16 v[104:107], v[148:151], v[172:175], v[104:107]
	v_mfma_f32_16x16x32_bf16 v[104:107], v[152:155], v[176:179], v[104:107]
	v_mfma_f32_16x16x32_bf16 v[100:103], v[156:159], v[172:175], v[100:103]
	v_mfma_f32_16x16x32_bf16 v[100:103], v[160:163], v[176:179], v[100:103]
	v_mfma_f32_16x16x32_bf16 v[88:91], v[148:151], v[180:183], v[88:91]
	v_mfma_f32_16x16x32_bf16 v[88:91], v[152:155], v[184:187], v[88:91]
	v_mfma_f32_16x16x32_bf16 v[84:87], v[156:159], v[180:183], v[84:87]
	v_mfma_f32_16x16x32_bf16 v[84:87], v[160:163], v[184:187], v[84:87]
	v_mfma_f32_16x16x32_bf16 v[72:75], v[148:151], v[196:199], v[72:75]
	v_mfma_f32_16x16x32_bf16 v[72:75], v[152:155], v[200:203], v[72:75]
	v_mfma_f32_16x16x32_bf16 v[68:71], v[156:159], v[196:199], v[68:71]
	v_mfma_f32_16x16x32_bf16 v[68:71], v[160:163], v[200:203], v[68:71]
	s_setprio 0
	s_barrier
	s_sleep 2
	s_add_i32 s16, s49, s2
	v_lshl_add_u64 v[204:205], s[20:21], 0, v[2:3]
	s_mov_b32 m0, s16
	ds_read_b128 v[164:167], v221 offset:16384
	ds_read_b128 v[168:171], v221 offset:17408
	ds_read_b128 v[172:175], v221 offset:18432
	ds_read_b128 v[176:179], v221 offset:19456
	ds_read_b128 v[180:183], v221 offset:20480
	ds_read_b128 v[184:187], v221 offset:21504
	ds_read_b128 v[196:199], v221 offset:22528
	ds_read_b128 v[200:203], v221 offset:23552
	global_load_lds_dwordx4 v[204:205], off
	s_add_i32 m0, s16, 0x2000
	s_add_u32 s16, s20, 0x160000
	v_lshl_add_u64 v[206:207], s[20:21], 0, v[190:191]
	s_addc_u32 s17, s21, 0
	s_add_i32 s49, s50, s2
	global_load_lds_dwordx4 v[206:207], off
	v_lshl_add_u64 v[208:209], s[16:17], 0, v[2:3]
	s_mov_b32 m0, s49
	v_lshl_add_u64 v[210:211], s[22:23], 0, v[188:189]
	global_load_lds_dwordx4 v[208:209], off
	v_lshl_add_u64 v[208:209], s[16:17], 0, v[190:191]
	s_add_i32 m0, s49, 0x2000
	s_nop 0
	global_load_lds_dwordx4 v[208:209], off
	v_lshl_add_u64 v[208:209], s[22:23], 0, v[0:1]
	s_mov_b32 m0, s28
	s_nop 0
	global_load_lds_dwordx4 v[208:209], off
	s_mov_b32 m0, s29
	s_nop 0
	global_load_lds_dwordx4 v[210:211], off
	s_waitcnt vmcnt(8)
	s_waitcnt lgkmcnt(0)
	s_barrier
	s_setprio 1
	s_waitcnt lgkmcnt(0)
	v_mfma_f32_16x16x32_bf16 v[64:67], v[124:127], v[164:167], v[64:67]
	v_mfma_f32_16x16x32_bf16 v[64:67], v[128:131], v[168:171], v[64:67]
	v_mfma_f32_16x16x32_bf16 v[60:63], v[140:143], v[164:167], v[60:63]
	v_mfma_f32_16x16x32_bf16 v[60:63], v[144:147], v[168:171], v[60:63]
	v_mfma_f32_16x16x32_bf16 v[48:51], v[124:127], v[172:175], v[48:51]
	v_mfma_f32_16x16x32_bf16 v[48:51], v[128:131], v[176:179], v[48:51]
	v_mfma_f32_16x16x32_bf16 v[44:47], v[140:143], v[172:175], v[44:47]
	v_mfma_f32_16x16x32_bf16 v[44:47], v[144:147], v[176:179], v[44:47]
	v_mfma_f32_16x16x32_bf16 v[32:35], v[124:127], v[180:183], v[32:35]
	v_mfma_f32_16x16x32_bf16 v[32:35], v[128:131], v[184:187], v[32:35]
	v_mfma_f32_16x16x32_bf16 v[28:31], v[140:143], v[180:183], v[28:31]
	v_mfma_f32_16x16x32_bf16 v[28:31], v[144:147], v[184:187], v[28:31]
	v_mfma_f32_16x16x32_bf16 v[16:19], v[124:127], v[196:199], v[16:19]
	v_mfma_f32_16x16x32_bf16 v[16:19], v[128:131], v[200:203], v[16:19]
	v_mfma_f32_16x16x32_bf16 v[12:15], v[140:143], v[196:199], v[12:15]
	v_mfma_f32_16x16x32_bf16 v[12:15], v[144:147], v[200:203], v[12:15]
	v_mfma_f32_16x16x32_bf16 v[56:59], v[148:151], v[164:167], v[56:59]
	v_mfma_f32_16x16x32_bf16 v[56:59], v[152:155], v[168:171], v[56:59]
	v_mfma_f32_16x16x32_bf16 v[52:55], v[156:159], v[164:167], v[52:55]
	v_mfma_f32_16x16x32_bf16 v[52:55], v[160:163], v[168:171], v[52:55]
	v_mfma_f32_16x16x32_bf16 v[40:43], v[148:151], v[172:175], v[40:43]
	v_mfma_f32_16x16x32_bf16 v[40:43], v[152:155], v[176:179], v[40:43]
	v_mfma_f32_16x16x32_bf16 v[36:39], v[156:159], v[172:175], v[36:39]
	v_mfma_f32_16x16x32_bf16 v[36:39], v[160:163], v[176:179], v[36:39]
	v_mfma_f32_16x16x32_bf16 v[24:27], v[148:151], v[180:183], v[24:27]
	v_mfma_f32_16x16x32_bf16 v[24:27], v[152:155], v[184:187], v[24:27]
	v_mfma_f32_16x16x32_bf16 v[20:23], v[156:159], v[180:183], v[20:23]
	v_mfma_f32_16x16x32_bf16 v[20:23], v[160:163], v[184:187], v[20:23]
	v_mfma_f32_16x16x32_bf16 v[8:11], v[148:151], v[196:199], v[8:11]
	v_mfma_f32_16x16x32_bf16 v[8:11], v[152:155], v[200:203], v[8:11]
	v_mfma_f32_16x16x32_bf16 v[4:7], v[156:159], v[196:199], v[4:7]
	v_mfma_f32_16x16x32_bf16 v[4:7], v[160:163], v[200:203], v[4:7]
	s_setprio 0
	s_barrier
	s_sleep 2
	s_add_i32 s49, 0, 0x18000
	s_add_i32 s50, 0, 0x1c000
	v_add_u32_e32 v144, s49, v219
	v_add_u32_e32 v160, s50, v219
	ds_read_b128 v[124:127], v144
	ds_read_b128 v[128:131], v144 offset:1024
	ds_read_b128 v[140:143], v144 offset:2048
	ds_read_b128 v[144:147], v144 offset:3072
	ds_read_b128 v[148:151], v160
	ds_read_b128 v[152:155], v160 offset:1024
	ds_read_b128 v[156:159], v160 offset:2048
	ds_read_b128 v[160:163], v160 offset:3072
	s_add_u32 s16, s22, 0x160000
	s_addc_u32 s17, s23, 0
	s_mov_b32 m0, s30
	v_lshl_add_u64 v[212:213], s[16:17], 0, v[0:1]
	ds_read_b128 v[164:167], v221 offset:32768
	ds_read_b128 v[168:171], v221 offset:33792
	ds_read_b128 v[172:175], v221 offset:34816
	ds_read_b128 v[176:179], v221 offset:35840
	ds_read_b128 v[180:183], v221 offset:36864
	ds_read_b128 v[184:187], v221 offset:37888
	ds_read_b128 v[196:199], v221 offset:38912
	ds_read_b128 v[200:203], v221 offset:39936
	global_load_lds_dwordx4 v[212:213], off
	v_lshl_add_u64 v[212:213], s[16:17], 0, v[188:189]
	s_mov_b32 m0, s31
	s_nop 0
	global_load_lds_dwordx4 v[212:213], off
	s_waitcnt vmcnt(8)
	s_waitcnt lgkmcnt(0)
	s_barrier
	s_setprio 1
	s_waitcnt lgkmcnt(0)
	v_mfma_f32_16x16x32_bf16 v[136:139], v[124:127], v[164:167], v[136:139]
	v_mfma_f32_16x16x32_bf16 v[136:139], v[128:131], v[168:171], v[136:139]
	v_mfma_f32_16x16x32_bf16 v[132:135], v[140:143], v[164:167], v[132:135]
	v_mfma_f32_16x16x32_bf16 v[132:135], v[144:147], v[168:171], v[132:135]
	v_mfma_f32_16x16x32_bf16 v[112:115], v[124:127], v[172:175], v[112:115]
	v_mfma_f32_16x16x32_bf16 v[112:115], v[128:131], v[176:179], v[112:115]
	v_mfma_f32_16x16x32_bf16 v[108:111], v[140:143], v[172:175], v[108:111]
	v_mfma_f32_16x16x32_bf16 v[108:111], v[144:147], v[176:179], v[108:111]
	v_mfma_f32_16x16x32_bf16 v[96:99], v[124:127], v[180:183], v[96:99]
	v_mfma_f32_16x16x32_bf16 v[96:99], v[128:131], v[184:187], v[96:99]
	v_mfma_f32_16x16x32_bf16 v[92:95], v[140:143], v[180:183], v[92:95]
	v_mfma_f32_16x16x32_bf16 v[92:95], v[144:147], v[184:187], v[92:95]
	v_mfma_f32_16x16x32_bf16 v[80:83], v[124:127], v[196:199], v[80:83]
	v_mfma_f32_16x16x32_bf16 v[80:83], v[128:131], v[200:203], v[80:83]
	v_mfma_f32_16x16x32_bf16 v[76:79], v[140:143], v[196:199], v[76:79]
	v_mfma_f32_16x16x32_bf16 v[76:79], v[144:147], v[200:203], v[76:79]
	v_mfma_f32_16x16x32_bf16 v[120:123], v[148:151], v[164:167], v[120:123]
	v_mfma_f32_16x16x32_bf16 v[120:123], v[152:155], v[168:171], v[120:123]
	v_mfma_f32_16x16x32_bf16 v[116:119], v[156:159], v[164:167], v[116:119]
	v_mfma_f32_16x16x32_bf16 v[116:119], v[160:163], v[168:171], v[116:119]
	v_mfma_f32_16x16x32_bf16 v[104:107], v[148:151], v[172:175], v[104:107]
	v_mfma_f32_16x16x32_bf16 v[104:107], v[152:155], v[176:179], v[104:107]
	v_mfma_f32_16x16x32_bf16 v[100:103], v[156:159], v[172:175], v[100:103]
	v_mfma_f32_16x16x32_bf16 v[100:103], v[160:163], v[176:179], v[100:103]
	v_mfma_f32_16x16x32_bf16 v[88:91], v[148:151], v[180:183], v[88:91]
	v_mfma_f32_16x16x32_bf16 v[88:91], v[152:155], v[184:187], v[88:91]
	v_mfma_f32_16x16x32_bf16 v[84:87], v[156:159], v[180:183], v[84:87]
	v_mfma_f32_16x16x32_bf16 v[84:87], v[160:163], v[184:187], v[84:87]
	v_mfma_f32_16x16x32_bf16 v[72:75], v[148:151], v[196:199], v[72:75]
	v_mfma_f32_16x16x32_bf16 v[72:75], v[152:155], v[200:203], v[72:75]
	v_mfma_f32_16x16x32_bf16 v[68:71], v[156:159], v[196:199], v[68:71]
	v_mfma_f32_16x16x32_bf16 v[68:71], v[160:163], v[200:203], v[68:71]
	s_setprio 0
	s_barrier
	s_sleep 2
	s_add_i32 s16, s49, s2
	v_lshl_add_u64 v[204:205], v[204:205], 0, s[66:67]
	s_mov_b32 m0, s16
	ds_read_b128 v[164:167], v221 offset:49152
	ds_read_b128 v[168:171], v221 offset:50176
	ds_read_b128 v[172:175], v221 offset:51200
	ds_read_b128 v[176:179], v221 offset:52224
	ds_read_b128 v[180:183], v221 offset:53248
	ds_read_b128 v[184:187], v221 offset:54272
	ds_read_b128 v[196:199], v221 offset:55296
	ds_read_b128 v[200:203], v221 offset:56320
	global_load_lds_dwordx4 v[204:205], off
	s_add_i32 m0, s16, 0x2000
	s_add_u32 s16, s20, 0x160080
	v_lshl_add_u64 v[204:205], v[206:207], 0, s[66:67]
	s_addc_u32 s17, s21, 0
	s_add_i32 s20, s50, s2
	global_load_lds_dwordx4 v[204:205], off
	v_lshl_add_u64 v[204:205], s[16:17], 0, v[2:3]
	s_mov_b32 m0, s20
	s_nop 0
	global_load_lds_dwordx4 v[204:205], off
	v_lshl_add_u64 v[204:205], s[16:17], 0, v[190:191]
	s_add_i32 m0, s20, 0x2000
	s_nop 0
	global_load_lds_dwordx4 v[204:205], off
	v_lshl_add_u64 v[204:205], v[208:209], 0, s[66:67]
	s_mov_b32 m0, s34
	s_nop 0
	global_load_lds_dwordx4 v[204:205], off
	v_lshl_add_u64 v[204:205], v[210:211], 0, s[66:67]
	s_mov_b32 m0, s35
	s_nop 0
	global_load_lds_dwordx4 v[204:205], off
	s_waitcnt vmcnt(8)
	s_waitcnt lgkmcnt(0)
	s_barrier
	s_setprio 1
	s_waitcnt lgkmcnt(0)
	v_mfma_f32_16x16x32_bf16 v[64:67], v[124:127], v[164:167], v[64:67]
	v_mfma_f32_16x16x32_bf16 v[64:67], v[128:131], v[168:171], v[64:67]
	v_mfma_f32_16x16x32_bf16 v[60:63], v[140:143], v[164:167], v[60:63]
	v_mfma_f32_16x16x32_bf16 v[60:63], v[144:147], v[168:171], v[60:63]
	v_mfma_f32_16x16x32_bf16 v[48:51], v[124:127], v[172:175], v[48:51]
	v_mfma_f32_16x16x32_bf16 v[48:51], v[128:131], v[176:179], v[48:51]
	v_mfma_f32_16x16x32_bf16 v[44:47], v[140:143], v[172:175], v[44:47]
	v_mfma_f32_16x16x32_bf16 v[44:47], v[144:147], v[176:179], v[44:47]
	v_mfma_f32_16x16x32_bf16 v[32:35], v[124:127], v[180:183], v[32:35]
	v_mfma_f32_16x16x32_bf16 v[32:35], v[128:131], v[184:187], v[32:35]
	v_mfma_f32_16x16x32_bf16 v[28:31], v[140:143], v[180:183], v[28:31]
	v_mfma_f32_16x16x32_bf16 v[28:31], v[144:147], v[184:187], v[28:31]
	v_mfma_f32_16x16x32_bf16 v[16:19], v[124:127], v[196:199], v[16:19]
	v_mfma_f32_16x16x32_bf16 v[16:19], v[128:131], v[200:203], v[16:19]
	v_mfma_f32_16x16x32_bf16 v[12:15], v[140:143], v[196:199], v[12:15]
	v_mfma_f32_16x16x32_bf16 v[12:15], v[144:147], v[200:203], v[12:15]
	v_mfma_f32_16x16x32_bf16 v[56:59], v[148:151], v[164:167], v[56:59]
	v_mfma_f32_16x16x32_bf16 v[56:59], v[152:155], v[168:171], v[56:59]
	v_mfma_f32_16x16x32_bf16 v[52:55], v[156:159], v[164:167], v[52:55]
	v_mfma_f32_16x16x32_bf16 v[52:55], v[160:163], v[168:171], v[52:55]
	v_mfma_f32_16x16x32_bf16 v[40:43], v[148:151], v[172:175], v[40:43]
	v_mfma_f32_16x16x32_bf16 v[40:43], v[152:155], v[176:179], v[40:43]
	v_mfma_f32_16x16x32_bf16 v[36:39], v[156:159], v[172:175], v[36:39]
	v_mfma_f32_16x16x32_bf16 v[36:39], v[160:163], v[176:179], v[36:39]
	v_mfma_f32_16x16x32_bf16 v[24:27], v[148:151], v[180:183], v[24:27]
	v_mfma_f32_16x16x32_bf16 v[24:27], v[152:155], v[184:187], v[24:27]
	v_mfma_f32_16x16x32_bf16 v[20:23], v[156:159], v[180:183], v[20:23]
	v_mfma_f32_16x16x32_bf16 v[20:23], v[160:163], v[184:187], v[20:23]
	v_mfma_f32_16x16x32_bf16 v[8:11], v[148:151], v[196:199], v[8:11]
	v_mfma_f32_16x16x32_bf16 v[8:11], v[152:155], v[200:203], v[8:11]
	v_mfma_f32_16x16x32_bf16 v[4:7], v[156:159], v[196:199], v[4:7]
	v_mfma_f32_16x16x32_bf16 v[4:7], v[160:163], v[200:203], v[4:7]
	s_setprio 0
	s_barrier
	s_add_i32 s48, s48, 2
	s_add_u32 s40, s40, 0x100
	s_addc_u32 s41, s41, 0
	s_cmpk_gt_u32 s48, 0x55
	s_mov_b64 s[16:17], s[18:19]
	s_cbranch_scc0 .LBB0_301
	s_and_b64 vcc, exec, s[10:11]
	s_cbranch_vccz .LBB0_304
	s_barrier

.LBB0_347:
	s_sleep 2
	s_add_u32 s16, s14, 0x100
	s_addc_u32 s17, s15, 0
	s_add_i32 s44, 0, 0x10000
	s_cmpk_eq_i32 s43, 0x54
	s_cselect_b32 s21, s11, s17
	s_cselect_b32 s20, s10, s16
	s_cselect_b32 s19, s13, s39
	s_cselect_b32 s18, s12, s38
	s_add_i32 s45, 0, 0x14000
	v_add_u32_e32 v144, s44, v236
	v_add_u32_e32 v160, s45, v236
	ds_read_b128 v[132:135], v144
	ds_read_b128 v[136:139], v144 offset:1024
	ds_read_b128 v[140:143], v144 offset:2048
	ds_read_b128 v[144:147], v144 offset:3072
	ds_read_b128 v[148:151], v160
	ds_read_b128 v[152:155], v160 offset:1024
	ds_read_b128 v[156:159], v160 offset:2048
	ds_read_b128 v[160:163], v160 offset:3072
	v_lshl_add_u64 v[204:205], s[14:15], 0, v[200:201]
	s_add_i32 m0, s23, 0xc000
	ds_read_b128 v[164:167], v238
	ds_read_b128 v[168:171], v238 offset:1024
	ds_read_b128 v[172:175], v238 offset:2048
	ds_read_b128 v[176:179], v238 offset:3072
	ds_read_b128 v[180:183], v238 offset:4096
	ds_read_b128 v[184:187], v238 offset:5120
	ds_read_b128 v[188:191], v238 offset:6144
	ds_read_b128 v[192:195], v238 offset:7168
	global_load_lds_dwordx4 v[204:205], off
	v_lshl_add_u64 v[204:205], s[14:15], 0, v[202:203]
	s_add_i32 m0, s23, 0xe000
	s_nop 0
	global_load_lds_dwordx4 v[204:205], off
	s_waitcnt vmcnt(8)
	s_waitcnt lgkmcnt(0)
	s_barrier
	s_setprio 1
	s_waitcnt lgkmcnt(0)
	v_mfma_f32_16x16x32_bf16 v[128:131], v[132:135], v[164:167], v[128:131]
	v_mfma_f32_16x16x32_bf16 v[128:131], v[136:139], v[168:171], v[128:131]
	v_mfma_f32_16x16x32_bf16 v[124:127], v[140:143], v[164:167], v[124:127]
	v_mfma_f32_16x16x32_bf16 v[124:127], v[144:147], v[168:171], v[124:127]
	v_mfma_f32_16x16x32_bf16 v[116:119], v[132:135], v[172:175], v[116:119]
	v_mfma_f32_16x16x32_bf16 v[116:119], v[136:139], v[176:179], v[116:119]
	v_mfma_f32_16x16x32_bf16 v[108:111], v[140:143], v[172:175], v[108:111]
	v_mfma_f32_16x16x32_bf16 v[108:111], v[144:147], v[176:179], v[108:111]
	v_mfma_f32_16x16x32_bf16 v[100:103], v[132:135], v[180:183], v[100:103]
	v_mfma_f32_16x16x32_bf16 v[100:103], v[136:139], v[184:187], v[100:103]
	v_mfma_f32_16x16x32_bf16 v[92:95], v[140:143], v[180:183], v[92:95]
	v_mfma_f32_16x16x32_bf16 v[92:95], v[144:147], v[184:187], v[92:95]
	v_mfma_f32_16x16x32_bf16 v[84:87], v[132:135], v[188:191], v[84:87]
	v_mfma_f32_16x16x32_bf16 v[84:87], v[136:139], v[192:195], v[84:87]
	v_mfma_f32_16x16x32_bf16 v[76:79], v[140:143], v[188:191], v[76:79]
	v_mfma_f32_16x16x32_bf16 v[76:79], v[144:147], v[192:195], v[76:79]
	v_mfma_f32_16x16x32_bf16 v[120:123], v[148:151], v[164:167], v[120:123]
	v_mfma_f32_16x16x32_bf16 v[120:123], v[152:155], v[168:171], v[120:123]
	v_mfma_f32_16x16x32_bf16 v[112:115], v[156:159], v[164:167], v[112:115]
	v_mfma_f32_16x16x32_bf16 v[112:115], v[160:163], v[168:171], v[112:115]
	v_mfma_f32_16x16x32_bf16 v[104:107], v[148:151], v[172:175], v[104:107]
	v_mfma_f32_16x16x32_bf16 v[104:107], v[152:155], v[176:179], v[104:107]
	v_mfma_f32_16x16x32_bf16 v[96:99], v[156:159], v[172:175], v[96:99]
	v_mfma_f32_16x16x32_bf16 v[96:99], v[160:163], v[176:179], v[96:99]
	v_mfma_f32_16x16x32_bf16 v[88:91], v[148:151], v[180:183], v[88:91]
	v_mfma_f32_16x16x32_bf16 v[88:91], v[152:155], v[184:187], v[88:91]
	v_mfma_f32_16x16x32_bf16 v[80:83], v[156:159], v[180:183], v[80:83]
	v_mfma_f32_16x16x32_bf16 v[80:83], v[160:163], v[184:187], v[80:83]
	v_mfma_f32_16x16x32_bf16 v[72:75], v[148:151], v[188:191], v[72:75]
	v_mfma_f32_16x16x32_bf16 v[72:75], v[152:155], v[192:195], v[72:75]
	v_mfma_f32_16x16x32_bf16 v[68:71], v[156:159], v[188:191], v[68:71]
	v_mfma_f32_16x16x32_bf16 v[68:71], v[160:163], v[192:195], v[68:71]
	s_setprio 0
	s_barrier
	s_sleep 2
	s_add_i32 s14, s44, s22
	v_lshl_add_u64 v[204:205], s[18:19], 0, v[2:3]
	s_mov_b32 m0, s14
	ds_read_b128 v[164:167], v238 offset:16384
	ds_read_b128 v[168:171], v238 offset:17408
	ds_read_b128 v[172:175], v238 offset:18432
	ds_read_b128 v[176:179], v238 offset:19456
	ds_read_b128 v[180:183], v238 offset:20480
	ds_read_b128 v[184:187], v238 offset:21504
	ds_read_b128 v[188:191], v238 offset:22528
	ds_read_b128 v[192:195], v238 offset:23552
	global_load_lds_dwordx4 v[204:205], off
	s_add_i32 m0, s14, 0x2000
	s_add_u32 s14, s18, 0x160000
	v_lshl_add_u64 v[206:207], s[18:19], 0, v[198:199]
	s_addc_u32 s15, s19, 0
	s_add_i32 s44, s45, s22
	global_load_lds_dwordx4 v[206:207], off
	v_lshl_add_u64 v[208:209], s[14:15], 0, v[2:3]
	s_mov_b32 m0, s44
	v_lshl_add_u64 v[210:211], s[20:21], 0, v[196:197]
	global_load_lds_dwordx4 v[208:209], off
	v_lshl_add_u64 v[208:209], s[14:15], 0, v[198:199]
	s_add_i32 m0, s44, 0x2000
	s_nop 0
	global_load_lds_dwordx4 v[208:209], off
	v_lshl_add_u64 v[208:209], s[20:21], 0, v[0:1]
	s_mov_b32 m0, s23
	s_nop 0
	global_load_lds_dwordx4 v[208:209], off
	s_mov_b32 m0, s28
	s_nop 0
	global_load_lds_dwordx4 v[210:211], off
	s_waitcnt vmcnt(8)
	s_waitcnt lgkmcnt(0)
	s_barrier
	s_setprio 1
	s_waitcnt lgkmcnt(0)
	v_mfma_f32_16x16x32_bf16 v[64:67], v[132:135], v[164:167], v[64:67]
	v_mfma_f32_16x16x32_bf16 v[64:67], v[136:139], v[168:171], v[64:67]
	v_mfma_f32_16x16x32_bf16 v[60:63], v[140:143], v[164:167], v[60:63]
	v_mfma_f32_16x16x32_bf16 v[60:63], v[144:147], v[168:171], v[60:63]
	v_mfma_f32_16x16x32_bf16 v[52:55], v[132:135], v[172:175], v[52:55]
	v_mfma_f32_16x16x32_bf16 v[52:55], v[136:139], v[176:179], v[52:55]
	v_mfma_f32_16x16x32_bf16 v[44:47], v[140:143], v[172:175], v[44:47]
	v_mfma_f32_16x16x32_bf16 v[44:47], v[144:147], v[176:179], v[44:47]
	v_mfma_f32_16x16x32_bf16 v[36:39], v[132:135], v[180:183], v[36:39]
	v_mfma_f32_16x16x32_bf16 v[36:39], v[136:139], v[184:187], v[36:39]
	v_mfma_f32_16x16x32_bf16 v[28:31], v[140:143], v[180:183], v[28:31]
	v_mfma_f32_16x16x32_bf16 v[28:31], v[144:147], v[184:187], v[28:31]
	v_mfma_f32_16x16x32_bf16 v[20:23], v[132:135], v[188:191], v[20:23]
	v_mfma_f32_16x16x32_bf16 v[20:23], v[136:139], v[192:195], v[20:23]
	v_mfma_f32_16x16x32_bf16 v[12:15], v[140:143], v[188:191], v[12:15]
	v_mfma_f32_16x16x32_bf16 v[12:15], v[144:147], v[192:195], v[12:15]
	v_mfma_f32_16x16x32_bf16 v[56:59], v[148:151], v[164:167], v[56:59]
	v_mfma_f32_16x16x32_bf16 v[56:59], v[152:155], v[168:171], v[56:59]
	v_mfma_f32_16x16x32_bf16 v[48:51], v[156:159], v[164:167], v[48:51]
	v_mfma_f32_16x16x32_bf16 v[48:51], v[160:163], v[168:171], v[48:51]
	v_mfma_f32_16x16x32_bf16 v[40:43], v[148:151], v[172:175], v[40:43]
	v_mfma_f32_16x16x32_bf16 v[40:43], v[152:155], v[176:179], v[40:43]
	v_mfma_f32_16x16x32_bf16 v[32:35], v[156:159], v[172:175], v[32:35]
	v_mfma_f32_16x16x32_bf16 v[32:35], v[160:163], v[176:179], v[32:35]
	v_mfma_f32_16x16x32_bf16 v[24:27], v[148:151], v[180:183], v[24:27]
	v_mfma_f32_16x16x32_bf16 v[24:27], v[152:155], v[184:187], v[24:27]
	v_mfma_f32_16x16x32_bf16 v[16:19], v[156:159], v[180:183], v[16:19]
	v_mfma_f32_16x16x32_bf16 v[16:19], v[160:163], v[184:187], v[16:19]
	v_mfma_f32_16x16x32_bf16 v[8:11], v[148:151], v[188:191], v[8:11]
	v_mfma_f32_16x16x32_bf16 v[8:11], v[152:155], v[192:195], v[8:11]
	v_mfma_f32_16x16x32_bf16 v[4:7], v[156:159], v[188:191], v[4:7]
	v_mfma_f32_16x16x32_bf16 v[4:7], v[160:163], v[192:195], v[4:7]
	s_setprio 0
	s_barrier
	s_sleep 2
	s_add_i32 s44, 0, 0x18000
	s_add_i32 s45, 0, 0x1c000
	v_add_u32_e32 v144, s44, v236
	v_add_u32_e32 v160, s45, v236
	ds_read_b128 v[132:135], v144
	ds_read_b128 v[136:139], v144 offset:1024
	ds_read_b128 v[140:143], v144 offset:2048
	ds_read_b128 v[144:147], v144 offset:3072
	ds_read_b128 v[148:151], v160
	ds_read_b128 v[152:155], v160 offset:1024
	ds_read_b128 v[156:159], v160 offset:2048
	ds_read_b128 v[160:163], v160 offset:3072
	s_add_u32 s14, s20, 0x160000
	s_addc_u32 s15, s21, 0
	s_mov_b32 m0, s29
	v_lshl_add_u64 v[212:213], s[14:15], 0, v[0:1]
	ds_read_b128 v[164:167], v238 offset:32768
	ds_read_b128 v[168:171], v238 offset:33792
	ds_read_b128 v[172:175], v238 offset:34816
	ds_read_b128 v[176:179], v238 offset:35840
	ds_read_b128 v[180:183], v238 offset:36864
	ds_read_b128 v[184:187], v238 offset:37888
	ds_read_b128 v[188:191], v238 offset:38912
	ds_read_b128 v[192:195], v238 offset:39936
	global_load_lds_dwordx4 v[212:213], off
	v_lshl_add_u64 v[212:213], s[14:15], 0, v[196:197]
	s_mov_b32 m0, s30
	s_nop 0
	global_load_lds_dwordx4 v[212:213], off
	s_waitcnt vmcnt(8)
	s_waitcnt lgkmcnt(0)
	s_barrier
	s_setprio 1
	s_waitcnt lgkmcnt(0)
	v_mfma_f32_16x16x32_bf16 v[128:131], v[132:135], v[164:167], v[128:131]
	v_mfma_f32_16x16x32_bf16 v[128:131], v[136:139], v[168:171], v[128:131]
	v_mfma_f32_16x16x32_bf16 v[124:127], v[140:143], v[164:167], v[124:127]
	v_mfma_f32_16x16x32_bf16 v[124:127], v[144:147], v[168:171], v[124:127]
	v_mfma_f32_16x16x32_bf16 v[116:119], v[132:135], v[172:175], v[116:119]
	v_mfma_f32_16x16x32_bf16 v[116:119], v[136:139], v[176:179], v[116:119]
	v_mfma_f32_16x16x32_bf16 v[108:111], v[140:143], v[172:175], v[108:111]
	v_mfma_f32_16x16x32_bf16 v[108:111], v[144:147], v[176:179], v[108:111]
	v_mfma_f32_16x16x32_bf16 v[100:103], v[132:135], v[180:183], v[100:103]
	v_mfma_f32_16x16x32_bf16 v[100:103], v[136:139], v[184:187], v[100:103]
	v_mfma_f32_16x16x32_bf16 v[92:95], v[140:143], v[180:183], v[92:95]
	v_mfma_f32_16x16x32_bf16 v[92:95], v[144:147], v[184:187], v[92:95]
	v_mfma_f32_16x16x32_bf16 v[84:87], v[132:135], v[188:191], v[84:87]
	v_mfma_f32_16x16x32_bf16 v[84:87], v[136:139], v[192:195], v[84:87]
	v_mfma_f32_16x16x32_bf16 v[76:79], v[140:143], v[188:191], v[76:79]
	v_mfma_f32_16x16x32_bf16 v[76:79], v[144:147], v[192:195], v[76:79]
	v_mfma_f32_16x16x32_bf16 v[120:123], v[148:151], v[164:167], v[120:123]
	v_mfma_f32_16x16x32_bf16 v[120:123], v[152:155], v[168:171], v[120:123]
	v_mfma_f32_16x16x32_bf16 v[112:115], v[156:159], v[164:167], v[112:115]
	v_mfma_f32_16x16x32_bf16 v[112:115], v[160:163], v[168:171], v[112:115]
	v_mfma_f32_16x16x32_bf16 v[104:107], v[148:151], v[172:175], v[104:107]
	v_mfma_f32_16x16x32_bf16 v[104:107], v[152:155], v[176:179], v[104:107]
	v_mfma_f32_16x16x32_bf16 v[96:99], v[156:159], v[172:175], v[96:99]
	v_mfma_f32_16x16x32_bf16 v[96:99], v[160:163], v[176:179], v[96:99]
	v_mfma_f32_16x16x32_bf16 v[88:91], v[148:151], v[180:183], v[88:91]
	v_mfma_f32_16x16x32_bf16 v[88:91], v[152:155], v[184:187], v[88:91]
	v_mfma_f32_16x16x32_bf16 v[80:83], v[156:159], v[180:183], v[80:83]
	v_mfma_f32_16x16x32_bf16 v[80:83], v[160:163], v[184:187], v[80:83]
	v_mfma_f32_16x16x32_bf16 v[72:75], v[148:151], v[188:191], v[72:75]
	v_mfma_f32_16x16x32_bf16 v[72:75], v[152:155], v[192:195], v[72:75]
	v_mfma_f32_16x16x32_bf16 v[68:71], v[156:159], v[188:191], v[68:71]
	v_mfma_f32_16x16x32_bf16 v[68:71], v[160:163], v[192:195], v[68:71]
	s_setprio 0
	s_barrier
	s_sleep 2
	s_add_i32 s14, s44, s22
	v_lshl_add_u64 v[204:205], v[204:205], 0, s[66:67]
	s_mov_b32 m0, s14
	ds_read_b128 v[164:167], v238 offset:49152
	ds_read_b128 v[168:171], v238 offset:50176
	ds_read_b128 v[172:175], v238 offset:51200
	ds_read_b128 v[176:179], v238 offset:52224
	ds_read_b128 v[180:183], v238 offset:53248
	ds_read_b128 v[184:187], v238 offset:54272
	ds_read_b128 v[188:191], v238 offset:55296
	ds_read_b128 v[192:195], v238 offset:56320
	global_load_lds_dwordx4 v[204:205], off
	s_add_i32 m0, s14, 0x2000
	s_add_u32 s14, s18, 0x160080
	v_lshl_add_u64 v[204:205], v[206:207], 0, s[66:67]
	s_addc_u32 s15, s19, 0
	s_add_i32 s18, s45, s22
	global_load_lds_dwordx4 v[204:205], off
	v_lshl_add_u64 v[204:205], s[14:15], 0, v[2:3]
	s_mov_b32 m0, s18
	s_nop 0
	global_load_lds_dwordx4 v[204:205], off
	v_lshl_add_u64 v[204:205], s[14:15], 0, v[198:199]
	s_add_i32 m0, s18, 0x2000
	s_nop 0
	global_load_lds_dwordx4 v[204:205], off
	v_lshl_add_u64 v[204:205], v[208:209], 0, s[66:67]
	s_mov_b32 m0, s31
	s_nop 0
	global_load_lds_dwordx4 v[204:205], off
	v_lshl_add_u64 v[204:205], v[210:211], 0, s[66:67]
	s_mov_b32 m0, s34
	s_nop 0
	global_load_lds_dwordx4 v[204:205], off
	s_waitcnt vmcnt(8)
	s_waitcnt lgkmcnt(0)
	s_barrier
	s_setprio 1
	s_waitcnt lgkmcnt(0)
	v_mfma_f32_16x16x32_bf16 v[64:67], v[132:135], v[164:167], v[64:67]
	v_mfma_f32_16x16x32_bf16 v[64:67], v[136:139], v[168:171], v[64:67]
	v_mfma_f32_16x16x32_bf16 v[60:63], v[140:143], v[164:167], v[60:63]
	v_mfma_f32_16x16x32_bf16 v[60:63], v[144:147], v[168:171], v[60:63]
	v_mfma_f32_16x16x32_bf16 v[52:55], v[132:135], v[172:175], v[52:55]
	v_mfma_f32_16x16x32_bf16 v[52:55], v[136:139], v[176:179], v[52:55]
	v_mfma_f32_16x16x32_bf16 v[44:47], v[140:143], v[172:175], v[44:47]
	v_mfma_f32_16x16x32_bf16 v[44:47], v[144:147], v[176:179], v[44:47]
	v_mfma_f32_16x16x32_bf16 v[36:39], v[132:135], v[180:183], v[36:39]
	v_mfma_f32_16x16x32_bf16 v[36:39], v[136:139], v[184:187], v[36:39]
	v_mfma_f32_16x16x32_bf16 v[28:31], v[140:143], v[180:183], v[28:31]
	v_mfma_f32_16x16x32_bf16 v[28:31], v[144:147], v[184:187], v[28:31]
	v_mfma_f32_16x16x32_bf16 v[20:23], v[132:135], v[188:191], v[20:23]
	v_mfma_f32_16x16x32_bf16 v[20:23], v[136:139], v[192:195], v[20:23]
	v_mfma_f32_16x16x32_bf16 v[12:15], v[140:143], v[188:191], v[12:15]
	v_mfma_f32_16x16x32_bf16 v[12:15], v[144:147], v[192:195], v[12:15]
	v_mfma_f32_16x16x32_bf16 v[56:59], v[148:151], v[164:167], v[56:59]
	v_mfma_f32_16x16x32_bf16 v[56:59], v[152:155], v[168:171], v[56:59]
	v_mfma_f32_16x16x32_bf16 v[48:51], v[156:159], v[164:167], v[48:51]
	v_mfma_f32_16x16x32_bf16 v[48:51], v[160:163], v[168:171], v[48:51]
	v_mfma_f32_16x16x32_bf16 v[40:43], v[148:151], v[172:175], v[40:43]
	v_mfma_f32_16x16x32_bf16 v[40:43], v[152:155], v[176:179], v[40:43]
	v_mfma_f32_16x16x32_bf16 v[32:35], v[156:159], v[172:175], v[32:35]
	v_mfma_f32_16x16x32_bf16 v[32:35], v[160:163], v[176:179], v[32:35]
	v_mfma_f32_16x16x32_bf16 v[24:27], v[148:151], v[180:183], v[24:27]
	v_mfma_f32_16x16x32_bf16 v[24:27], v[152:155], v[184:187], v[24:27]
	v_mfma_f32_16x16x32_bf16 v[16:19], v[156:159], v[180:183], v[16:19]
	v_mfma_f32_16x16x32_bf16 v[16:19], v[160:163], v[184:187], v[16:19]
	v_mfma_f32_16x16x32_bf16 v[8:11], v[148:151], v[188:191], v[8:11]
	v_mfma_f32_16x16x32_bf16 v[8:11], v[152:155], v[192:195], v[8:11]
	v_mfma_f32_16x16x32_bf16 v[4:7], v[156:159], v[188:191], v[4:7]
	v_mfma_f32_16x16x32_bf16 v[4:7], v[160:163], v[192:195], v[4:7]
	s_setprio 0
	s_barrier
	s_add_i32 s43, s43, 2
	s_add_u32 s38, s38, 0x100
	s_addc_u32 s39, s39, 0
	s_cmpk_gt_u32 s43, 0x55
	s_mov_b64 s[14:15], s[16:17]
	s_cbranch_scc0 .LBB0_347
	s_and_b64 vcc, exec, s[6:7]
	s_cbranch_vccz .LBB0_350
	s_barrier

.LBB0_430:
	s_sleep 2
	s_add_u32 s30, s28, 0xfff80080
	s_addc_u32 s31, s29, -1
	s_add_i32 s70, 0, 0x10000
	s_cmp_eq_u32 s69, 28
	s_cselect_b32 s43, s5, s31
	s_cselect_b32 s42, s23, s30
	s_cselect_b32 s31, s21, s68
	s_cselect_b32 s30, s62, s63
	s_add_i32 s73, 0, 0x14000
	s_waitcnt lgkmcnt(0)
	v_add_u32_e32 v152, s70, v163
	v_add_u32_e32 v160, s73, v163
	ds_read_b128 v[132:135], v152
	ds_read_b128 v[136:139], v152 offset:1024
	ds_read_b128 v[148:151], v152 offset:2048
	ds_read_b128 v[152:155], v152 offset:3072
	ds_read_b128 v[156:159], v160
	ds_read_b128 v[170:173], v160 offset:1024
	ds_read_b128 v[174:177], v160 offset:2048
	ds_read_b128 v[178:181], v160 offset:3072
	v_lshl_add_u64 v[160:161], s[28:29], 0, v[144:145]
	s_add_i32 m0, s15, 0xc000
	ds_read_b128 v[182:185], v167
	ds_read_b128 v[186:189], v167 offset:1024
	ds_read_b128 v[190:193], v167 offset:2048
	ds_read_b128 v[194:197], v167 offset:3072
	ds_read_b128 v[198:201], v167 offset:4096
	ds_read_b128 v[208:211], v167 offset:5120
	ds_read_b128 v[212:215], v167 offset:6144
	ds_read_b128 v[216:219], v167 offset:7168
	global_load_lds_dwordx4 v[160:161], off
	v_lshl_add_u64 v[160:161], s[28:29], 0, v[146:147]
	s_add_i32 m0, s15, 0xe000
	s_nop 0
	global_load_lds_dwordx4 v[160:161], off
	s_waitcnt vmcnt(8)
	s_waitcnt lgkmcnt(0)
	s_barrier
	s_setprio 1
	s_waitcnt lgkmcnt(0)
	v_mfma_f32_16x16x32_bf16 v[128:131], v[132:135], v[182:185], v[128:131]
	v_mfma_f32_16x16x32_bf16 v[128:131], v[136:139], v[186:189], v[128:131]
	v_mfma_f32_16x16x32_bf16 v[124:127], v[148:151], v[182:185], v[124:127]
	v_mfma_f32_16x16x32_bf16 v[124:127], v[152:155], v[186:189], v[124:127]
	v_mfma_f32_16x16x32_bf16 v[120:123], v[132:135], v[190:193], v[120:123]
	v_mfma_f32_16x16x32_bf16 v[120:123], v[136:139], v[194:197], v[120:123]
	v_mfma_f32_16x16x32_bf16 v[112:115], v[148:151], v[190:193], v[112:115]
	v_mfma_f32_16x16x32_bf16 v[112:115], v[152:155], v[194:197], v[112:115]
	v_mfma_f32_16x16x32_bf16 v[104:107], v[132:135], v[198:201], v[104:107]
	v_mfma_f32_16x16x32_bf16 v[104:107], v[136:139], v[208:211], v[104:107]
	v_mfma_f32_16x16x32_bf16 v[96:99], v[148:151], v[198:201], v[96:99]
	v_mfma_f32_16x16x32_bf16 v[96:99], v[152:155], v[208:211], v[96:99]
	v_mfma_f32_16x16x32_bf16 v[88:91], v[132:135], v[212:215], v[88:91]
	v_mfma_f32_16x16x32_bf16 v[88:91], v[136:139], v[216:219], v[88:91]
	v_mfma_f32_16x16x32_bf16 v[80:83], v[148:151], v[212:215], v[80:83]
	v_mfma_f32_16x16x32_bf16 v[80:83], v[152:155], v[216:219], v[80:83]
	v_mfma_f32_16x16x32_bf16 v[116:119], v[156:159], v[182:185], v[116:119]
	v_mfma_f32_16x16x32_bf16 v[116:119], v[170:173], v[186:189], v[116:119]
	v_mfma_f32_16x16x32_bf16 v[108:111], v[174:177], v[182:185], v[108:111]
	v_mfma_f32_16x16x32_bf16 v[108:111], v[178:181], v[186:189], v[108:111]
	v_mfma_f32_16x16x32_bf16 v[100:103], v[156:159], v[190:193], v[100:103]
	v_mfma_f32_16x16x32_bf16 v[100:103], v[170:173], v[194:197], v[100:103]
	v_mfma_f32_16x16x32_bf16 v[92:95], v[174:177], v[190:193], v[92:95]
	v_mfma_f32_16x16x32_bf16 v[92:95], v[178:181], v[194:197], v[92:95]
	v_mfma_f32_16x16x32_bf16 v[84:87], v[156:159], v[198:201], v[84:87]
	v_mfma_f32_16x16x32_bf16 v[84:87], v[170:173], v[208:211], v[84:87]
	v_mfma_f32_16x16x32_bf16 v[76:79], v[174:177], v[198:201], v[76:79]
	v_mfma_f32_16x16x32_bf16 v[76:79], v[178:181], v[208:211], v[76:79]
	v_mfma_f32_16x16x32_bf16 v[72:75], v[156:159], v[212:215], v[72:75]
	v_mfma_f32_16x16x32_bf16 v[72:75], v[170:173], v[216:219], v[72:75]
	v_mfma_f32_16x16x32_bf16 v[68:71], v[174:177], v[212:215], v[68:71]
	v_mfma_f32_16x16x32_bf16 v[68:71], v[178:181], v[216:219], v[68:71]
	s_setprio 0
	s_barrier
	s_sleep 2
	s_add_i32 s70, s70, s0
	v_lshl_add_u64 v[160:161], s[30:31], 0, v[2:3]
	s_mov_b32 m0, s70
	ds_read_b128 v[182:185], v167 offset:16384
	ds_read_b128 v[186:189], v167 offset:17408
	ds_read_b128 v[190:193], v167 offset:18432
	ds_read_b128 v[194:197], v167 offset:19456
	ds_read_b128 v[198:201], v167 offset:20480
	ds_read_b128 v[208:211], v167 offset:21504
	ds_read_b128 v[212:215], v167 offset:22528
	ds_read_b128 v[216:219], v167 offset:23552
	global_load_lds_dwordx4 v[160:161], off
	s_add_i32 m0, s70, 0x2000
	s_add_u32 s70, s30, 0x80000
	v_lshl_add_u64 v[202:203], s[30:31], 0, v[142:143]
	s_addc_u32 s71, s31, 0
	s_add_i32 s73, s73, s0
	global_load_lds_dwordx4 v[202:203], off
	v_lshl_add_u64 v[204:205], s[70:71], 0, v[2:3]
	s_mov_b32 m0, s73
	v_lshl_add_u64 v[206:207], s[42:43], 0, v[140:141]
	global_load_lds_dwordx4 v[204:205], off
	v_lshl_add_u64 v[204:205], s[70:71], 0, v[142:143]
	s_add_i32 m0, s73, 0x2000
	s_nop 0
	global_load_lds_dwordx4 v[204:205], off
	v_lshl_add_u64 v[204:205], s[42:43], 0, v[0:1]
	s_mov_b32 m0, s15
	s_nop 0
	global_load_lds_dwordx4 v[204:205], off
	s_mov_b32 m0, s53
	s_nop 0
	global_load_lds_dwordx4 v[206:207], off
	s_waitcnt vmcnt(8)
	s_waitcnt lgkmcnt(0)
	s_barrier
	s_setprio 1
	s_waitcnt lgkmcnt(0)
	v_mfma_f32_16x16x32_bf16 v[64:67], v[132:135], v[182:185], v[64:67]
	v_mfma_f32_16x16x32_bf16 v[64:67], v[136:139], v[186:189], v[64:67]
	v_mfma_f32_16x16x32_bf16 v[60:63], v[148:151], v[182:185], v[60:63]
	v_mfma_f32_16x16x32_bf16 v[60:63], v[152:155], v[186:189], v[60:63]
	v_mfma_f32_16x16x32_bf16 v[56:59], v[132:135], v[190:193], v[56:59]
	v_mfma_f32_16x16x32_bf16 v[56:59], v[136:139], v[194:197], v[56:59]
	v_mfma_f32_16x16x32_bf16 v[48:51], v[148:151], v[190:193], v[48:51]
	v_mfma_f32_16x16x32_bf16 v[48:51], v[152:155], v[194:197], v[48:51]
	v_mfma_f32_16x16x32_bf16 v[40:43], v[132:135], v[198:201], v[40:43]
	v_mfma_f32_16x16x32_bf16 v[40:43], v[136:139], v[208:211], v[40:43]
	v_mfma_f32_16x16x32_bf16 v[32:35], v[148:151], v[198:201], v[32:35]
	v_mfma_f32_16x16x32_bf16 v[32:35], v[152:155], v[208:211], v[32:35]
	v_mfma_f32_16x16x32_bf16 v[24:27], v[132:135], v[212:215], v[24:27]
	v_mfma_f32_16x16x32_bf16 v[24:27], v[136:139], v[216:219], v[24:27]
	v_mfma_f32_16x16x32_bf16 v[16:19], v[148:151], v[212:215], v[16:19]
	v_mfma_f32_16x16x32_bf16 v[16:19], v[152:155], v[216:219], v[16:19]
	v_mfma_f32_16x16x32_bf16 v[52:55], v[156:159], v[182:185], v[52:55]
	v_mfma_f32_16x16x32_bf16 v[52:55], v[170:173], v[186:189], v[52:55]
	v_mfma_f32_16x16x32_bf16 v[44:47], v[174:177], v[182:185], v[44:47]
	v_mfma_f32_16x16x32_bf16 v[44:47], v[178:181], v[186:189], v[44:47]
	v_mfma_f32_16x16x32_bf16 v[36:39], v[156:159], v[190:193], v[36:39]
	v_mfma_f32_16x16x32_bf16 v[36:39], v[170:173], v[194:197], v[36:39]
	v_mfma_f32_16x16x32_bf16 v[28:31], v[174:177], v[190:193], v[28:31]
	v_mfma_f32_16x16x32_bf16 v[28:31], v[178:181], v[194:197], v[28:31]
	v_mfma_f32_16x16x32_bf16 v[20:23], v[156:159], v[198:201], v[20:23]
	v_mfma_f32_16x16x32_bf16 v[20:23], v[170:173], v[208:211], v[20:23]
	v_mfma_f32_16x16x32_bf16 v[12:15], v[174:177], v[198:201], v[12:15]
	v_mfma_f32_16x16x32_bf16 v[12:15], v[178:181], v[208:211], v[12:15]
	v_mfma_f32_16x16x32_bf16 v[8:11], v[156:159], v[212:215], v[8:11]
	v_mfma_f32_16x16x32_bf16 v[8:11], v[170:173], v[216:219], v[8:11]
	v_mfma_f32_16x16x32_bf16 v[4:7], v[174:177], v[212:215], v[4:7]
	v_mfma_f32_16x16x32_bf16 v[4:7], v[178:181], v[216:219], v[4:7]
	s_setprio 0
	s_barrier
	s_sleep 2
	s_add_i32 s70, 0, 0x18000
	s_add_i32 s71, 0, 0x1c000
	v_add_u32_e32 v152, s70, v163
	v_add_u32_e32 v178, s71, v163
	ds_read_b128 v[132:135], v152
	ds_read_b128 v[136:139], v152 offset:1024
	ds_read_b128 v[148:151], v152 offset:2048
	ds_read_b128 v[152:155], v152 offset:3072
	ds_read_b128 v[156:159], v178
	ds_read_b128 v[170:173], v178 offset:1024
	ds_read_b128 v[174:177], v178 offset:2048
	ds_read_b128 v[178:181], v178 offset:3072
	s_add_u32 s42, s42, 0x80000
	s_addc_u32 s43, s43, 0
	s_mov_b32 m0, s54
	v_lshl_add_u64 v[220:221], s[42:43], 0, v[0:1]
	ds_read_b128 v[182:185], v167 offset:32768
	ds_read_b128 v[186:189], v167 offset:33792
	ds_read_b128 v[190:193], v167 offset:34816
	ds_read_b128 v[194:197], v167 offset:35840
	ds_read_b128 v[198:201], v167 offset:36864
	ds_read_b128 v[208:211], v167 offset:37888
	ds_read_b128 v[212:215], v167 offset:38912
	ds_read_b128 v[216:219], v167 offset:39936
	global_load_lds_dwordx4 v[220:221], off
	v_lshl_add_u64 v[220:221], s[42:43], 0, v[140:141]
	s_mov_b32 m0, s55
	s_nop 0
	global_load_lds_dwordx4 v[220:221], off
	s_waitcnt vmcnt(8)
	s_waitcnt lgkmcnt(0)
	s_barrier
	s_setprio 1
	s_waitcnt lgkmcnt(0)
	v_mfma_f32_16x16x32_bf16 v[128:131], v[132:135], v[182:185], v[128:131]
	v_mfma_f32_16x16x32_bf16 v[128:131], v[136:139], v[186:189], v[128:131]
	v_mfma_f32_16x16x32_bf16 v[124:127], v[148:151], v[182:185], v[124:127]
	v_mfma_f32_16x16x32_bf16 v[124:127], v[152:155], v[186:189], v[124:127]
	v_mfma_f32_16x16x32_bf16 v[120:123], v[132:135], v[190:193], v[120:123]
	v_mfma_f32_16x16x32_bf16 v[120:123], v[136:139], v[194:197], v[120:123]
	v_mfma_f32_16x16x32_bf16 v[112:115], v[148:151], v[190:193], v[112:115]
	v_mfma_f32_16x16x32_bf16 v[112:115], v[152:155], v[194:197], v[112:115]
	v_mfma_f32_16x16x32_bf16 v[104:107], v[132:135], v[198:201], v[104:107]
	v_mfma_f32_16x16x32_bf16 v[104:107], v[136:139], v[208:211], v[104:107]
	v_mfma_f32_16x16x32_bf16 v[96:99], v[148:151], v[198:201], v[96:99]
	v_mfma_f32_16x16x32_bf16 v[96:99], v[152:155], v[208:211], v[96:99]
	v_mfma_f32_16x16x32_bf16 v[88:91], v[132:135], v[212:215], v[88:91]
	v_mfma_f32_16x16x32_bf16 v[88:91], v[136:139], v[216:219], v[88:91]
	v_mfma_f32_16x16x32_bf16 v[80:83], v[148:151], v[212:215], v[80:83]
	v_mfma_f32_16x16x32_bf16 v[80:83], v[152:155], v[216:219], v[80:83]
	v_mfma_f32_16x16x32_bf16 v[116:119], v[156:159], v[182:185], v[116:119]
	v_mfma_f32_16x16x32_bf16 v[116:119], v[170:173], v[186:189], v[116:119]
	v_mfma_f32_16x16x32_bf16 v[108:111], v[174:177], v[182:185], v[108:111]
	v_mfma_f32_16x16x32_bf16 v[108:111], v[178:181], v[186:189], v[108:111]
	v_mfma_f32_16x16x32_bf16 v[100:103], v[156:159], v[190:193], v[100:103]
	v_mfma_f32_16x16x32_bf16 v[100:103], v[170:173], v[194:197], v[100:103]
	v_mfma_f32_16x16x32_bf16 v[92:95], v[174:177], v[190:193], v[92:95]
	v_mfma_f32_16x16x32_bf16 v[92:95], v[178:181], v[194:197], v[92:95]
	v_mfma_f32_16x16x32_bf16 v[84:87], v[156:159], v[198:201], v[84:87]
	v_mfma_f32_16x16x32_bf16 v[84:87], v[170:173], v[208:211], v[84:87]
	v_mfma_f32_16x16x32_bf16 v[76:79], v[174:177], v[198:201], v[76:79]
	v_mfma_f32_16x16x32_bf16 v[76:79], v[178:181], v[208:211], v[76:79]
	v_mfma_f32_16x16x32_bf16 v[72:75], v[156:159], v[212:215], v[72:75]
	v_mfma_f32_16x16x32_bf16 v[72:75], v[170:173], v[216:219], v[72:75]
	v_mfma_f32_16x16x32_bf16 v[68:71], v[174:177], v[212:215], v[68:71]
	v_mfma_f32_16x16x32_bf16 v[68:71], v[178:181], v[216:219], v[68:71]
	s_setprio 0
	s_barrier
	s_sleep 2
	s_add_i32 s42, s70, s0
	v_lshl_add_u64 v[160:161], v[160:161], 0, s[66:67]
	s_mov_b32 m0, s42
	ds_read_b128 v[182:185], v167 offset:49152
	ds_read_b128 v[186:189], v167 offset:50176
	ds_read_b128 v[190:193], v167 offset:51200
	ds_read_b128 v[194:197], v167 offset:52224
	ds_read_b128 v[198:201], v167 offset:53248
	ds_read_b128 v[208:211], v167 offset:54272
	ds_read_b128 v[212:215], v167 offset:55296
	ds_read_b128 v[216:219], v167 offset:56320
	global_load_lds_dwordx4 v[160:161], off
	s_add_i32 m0, s42, 0x2000
	s_add_u32 s30, s30, 0x80080
	v_lshl_add_u64 v[160:161], v[202:203], 0, s[66:67]
	s_addc_u32 s31, s31, 0
	s_add_i32 s42, s71, s0
	global_load_lds_dwordx4 v[160:161], off
	v_lshl_add_u64 v[160:161], s[30:31], 0, v[2:3]
	s_mov_b32 m0, s42
	s_nop 0
	global_load_lds_dwordx4 v[160:161], off
	v_lshl_add_u64 v[160:161], s[30:31], 0, v[142:143]
	s_add_i32 m0, s42, 0x2000
	s_nop 0
	global_load_lds_dwordx4 v[160:161], off
	v_lshl_add_u64 v[160:161], v[204:205], 0, s[66:67]
	s_mov_b32 m0, s60
	s_nop 0
	global_load_lds_dwordx4 v[160:161], off
	v_lshl_add_u64 v[160:161], v[206:207], 0, s[66:67]
	s_mov_b32 m0, s64
	s_nop 0
	global_load_lds_dwordx4 v[160:161], off
	s_waitcnt vmcnt(8)
	s_waitcnt lgkmcnt(0)
	s_barrier
	s_setprio 1
	s_waitcnt lgkmcnt(0)
	v_mfma_f32_16x16x32_bf16 v[64:67], v[132:135], v[182:185], v[64:67]
	v_mfma_f32_16x16x32_bf16 v[64:67], v[136:139], v[186:189], v[64:67]
	v_mfma_f32_16x16x32_bf16 v[60:63], v[148:151], v[182:185], v[60:63]
	v_mfma_f32_16x16x32_bf16 v[60:63], v[152:155], v[186:189], v[60:63]
	v_mfma_f32_16x16x32_bf16 v[56:59], v[132:135], v[190:193], v[56:59]
	v_mfma_f32_16x16x32_bf16 v[56:59], v[136:139], v[194:197], v[56:59]
	v_mfma_f32_16x16x32_bf16 v[48:51], v[148:151], v[190:193], v[48:51]
	v_mfma_f32_16x16x32_bf16 v[48:51], v[152:155], v[194:197], v[48:51]
	v_mfma_f32_16x16x32_bf16 v[40:43], v[132:135], v[198:201], v[40:43]
	v_mfma_f32_16x16x32_bf16 v[40:43], v[136:139], v[208:211], v[40:43]
	v_mfma_f32_16x16x32_bf16 v[32:35], v[148:151], v[198:201], v[32:35]
	v_mfma_f32_16x16x32_bf16 v[32:35], v[152:155], v[208:211], v[32:35]
	v_mfma_f32_16x16x32_bf16 v[24:27], v[132:135], v[212:215], v[24:27]
	v_mfma_f32_16x16x32_bf16 v[24:27], v[136:139], v[216:219], v[24:27]
	v_mfma_f32_16x16x32_bf16 v[16:19], v[148:151], v[212:215], v[16:19]
	v_mfma_f32_16x16x32_bf16 v[16:19], v[152:155], v[216:219], v[16:19]
	v_mfma_f32_16x16x32_bf16 v[52:55], v[156:159], v[182:185], v[52:55]
	v_mfma_f32_16x16x32_bf16 v[52:55], v[170:173], v[186:189], v[52:55]
	v_mfma_f32_16x16x32_bf16 v[44:47], v[174:177], v[182:185], v[44:47]
	v_mfma_f32_16x16x32_bf16 v[44:47], v[178:181], v[186:189], v[44:47]
	v_mfma_f32_16x16x32_bf16 v[36:39], v[156:159], v[190:193], v[36:39]
	v_mfma_f32_16x16x32_bf16 v[36:39], v[170:173], v[194:197], v[36:39]
	v_mfma_f32_16x16x32_bf16 v[28:31], v[174:177], v[190:193], v[28:31]
	v_mfma_f32_16x16x32_bf16 v[28:31], v[178:181], v[194:197], v[28:31]
	v_mfma_f32_16x16x32_bf16 v[20:23], v[156:159], v[198:201], v[20:23]
	v_mfma_f32_16x16x32_bf16 v[20:23], v[170:173], v[208:211], v[20:23]
	v_mfma_f32_16x16x32_bf16 v[12:15], v[174:177], v[198:201], v[12:15]
	v_mfma_f32_16x16x32_bf16 v[12:15], v[178:181], v[208:211], v[12:15]
	v_mfma_f32_16x16x32_bf16 v[8:11], v[156:159], v[212:215], v[8:11]
	v_mfma_f32_16x16x32_bf16 v[8:11], v[170:173], v[216:219], v[8:11]
	v_mfma_f32_16x16x32_bf16 v[4:7], v[174:177], v[212:215], v[4:7]
	v_mfma_f32_16x16x32_bf16 v[4:7], v[178:181], v[216:219], v[4:7]
	s_setprio 0
	s_barrier
	s_add_i32 s69, s69, 2
	s_add_u32 s28, s28, 0x100
	s_addc_u32 s29, s29, 0
	s_add_u32 s63, s63, 0x100
	s_addc_u32 s68, s68, 0
	s_cmp_gt_u32 s69, 29
	s_cbranch_scc0 .LBB0_430
	s_and_b64 vcc, exec, s[8:9]
	s_cbranch_vccz .LBB0_433
	s_barrier

.LBB0_495:
	s_sleep 2
	s_add_u32 s22, s20, 0xfff80080
	s_addc_u32 s23, s21, -1
	s_add_i32 s48, 0, 0x10000
	s_cmp_eq_u32 s47, 28
	s_cselect_b32 s25, s15, s23
	s_cselect_b32 s24, s43, s22
	s_cselect_b32 s23, s11, s46
	s_cselect_b32 s22, s44, s45
	s_add_i32 s50, 0, 0x14000
	s_waitcnt lgkmcnt(0)
	v_add_u32_e32 v152, s48, v137
	v_add_u32_e32 v168, s50, v137
	ds_read_b128 v[140:143], v152
	ds_read_b128 v[144:147], v152 offset:1024
	ds_read_b128 v[148:151], v152 offset:2048
	ds_read_b128 v[152:155], v152 offset:3072
	ds_read_b128 v[156:159], v168
	ds_read_b128 v[160:163], v168 offset:1024
	ds_read_b128 v[164:167], v168 offset:2048
	ds_read_b128 v[168:171], v168 offset:3072
	v_lshl_add_u64 v[204:205], s[20:21], 0, v[132:133]
	s_add_i32 m0, s31, 0xc000
	ds_read_b128 v[172:175], v139
	ds_read_b128 v[176:179], v139 offset:1024
	ds_read_b128 v[180:183], v139 offset:2048
	ds_read_b128 v[184:187], v139 offset:3072
	ds_read_b128 v[188:191], v139 offset:4096
	ds_read_b128 v[192:195], v139 offset:5120
	ds_read_b128 v[196:199], v139 offset:6144
	ds_read_b128 v[200:203], v139 offset:7168
	global_load_lds_dwordx4 v[204:205], off
	v_lshl_add_u64 v[204:205], s[20:21], 0, v[134:135]
	s_add_i32 m0, s31, 0xe000
	s_nop 0
	global_load_lds_dwordx4 v[204:205], off
	s_waitcnt vmcnt(8)
	s_waitcnt lgkmcnt(0)
	s_barrier
	s_setprio 1
	s_waitcnt lgkmcnt(0)
	v_mfma_f32_16x16x32_bf16 v[128:131], v[140:143], v[172:175], v[128:131]
	v_mfma_f32_16x16x32_bf16 v[128:131], v[144:147], v[176:179], v[128:131]
	v_mfma_f32_16x16x32_bf16 v[124:127], v[148:151], v[172:175], v[124:127]
	v_mfma_f32_16x16x32_bf16 v[124:127], v[152:155], v[176:179], v[124:127]
	v_mfma_f32_16x16x32_bf16 v[120:123], v[140:143], v[180:183], v[120:123]
	v_mfma_f32_16x16x32_bf16 v[120:123], v[144:147], v[184:187], v[120:123]
	v_mfma_f32_16x16x32_bf16 v[116:119], v[148:151], v[180:183], v[116:119]
	v_mfma_f32_16x16x32_bf16 v[116:119], v[152:155], v[184:187], v[116:119]
	v_mfma_f32_16x16x32_bf16 v[108:111], v[140:143], v[188:191], v[108:111]
	v_mfma_f32_16x16x32_bf16 v[108:111], v[144:147], v[192:195], v[108:111]
	v_mfma_f32_16x16x32_bf16 v[100:103], v[148:151], v[188:191], v[100:103]
	v_mfma_f32_16x16x32_bf16 v[100:103], v[152:155], v[192:195], v[100:103]
	v_mfma_f32_16x16x32_bf16 v[92:95], v[140:143], v[196:199], v[92:95]
	v_mfma_f32_16x16x32_bf16 v[92:95], v[144:147], v[200:203], v[92:95]
	v_mfma_f32_16x16x32_bf16 v[84:87], v[148:151], v[196:199], v[84:87]
	v_mfma_f32_16x16x32_bf16 v[84:87], v[152:155], v[200:203], v[84:87]
	v_mfma_f32_16x16x32_bf16 v[112:115], v[156:159], v[172:175], v[112:115]
	v_mfma_f32_16x16x32_bf16 v[112:115], v[160:163], v[176:179], v[112:115]
	v_mfma_f32_16x16x32_bf16 v[104:107], v[164:167], v[172:175], v[104:107]
	v_mfma_f32_16x16x32_bf16 v[104:107], v[168:171], v[176:179], v[104:107]
	v_mfma_f32_16x16x32_bf16 v[96:99], v[156:159], v[180:183], v[96:99]
	v_mfma_f32_16x16x32_bf16 v[96:99], v[160:163], v[184:187], v[96:99]
	v_mfma_f32_16x16x32_bf16 v[88:91], v[164:167], v[180:183], v[88:91]
	v_mfma_f32_16x16x32_bf16 v[88:91], v[168:171], v[184:187], v[88:91]
	v_mfma_f32_16x16x32_bf16 v[80:83], v[156:159], v[188:191], v[80:83]
	v_mfma_f32_16x16x32_bf16 v[80:83], v[160:163], v[192:195], v[80:83]
	v_mfma_f32_16x16x32_bf16 v[76:79], v[164:167], v[188:191], v[76:79]
	v_mfma_f32_16x16x32_bf16 v[76:79], v[168:171], v[192:195], v[76:79]
	v_mfma_f32_16x16x32_bf16 v[72:75], v[156:159], v[196:199], v[72:75]
	v_mfma_f32_16x16x32_bf16 v[72:75], v[160:163], v[200:203], v[72:75]
	v_mfma_f32_16x16x32_bf16 v[68:71], v[164:167], v[196:199], v[68:71]
	v_mfma_f32_16x16x32_bf16 v[68:71], v[168:171], v[200:203], v[68:71]
	s_setprio 0
	s_barrier
	s_sleep 2
	s_add_i32 s48, s48, s0
	v_lshl_add_u64 v[204:205], s[22:23], 0, v[2:3]
	s_mov_b32 m0, s48
	ds_read_b128 v[172:175], v139 offset:16384
	ds_read_b128 v[176:179], v139 offset:17408
	ds_read_b128 v[180:183], v139 offset:18432
	ds_read_b128 v[184:187], v139 offset:19456
	ds_read_b128 v[188:191], v139 offset:20480
	ds_read_b128 v[192:195], v139 offset:21504
	ds_read_b128 v[196:199], v139 offset:22528
	ds_read_b128 v[200:203], v139 offset:23552
	global_load_lds_dwordx4 v[204:205], off
	s_add_i32 m0, s48, 0x2000
	s_add_u32 s48, s22, 0x80000
	v_lshl_add_u64 v[206:207], s[22:23], 0, v[0:1]
	s_addc_u32 s49, s23, 0
	s_add_i32 s50, s50, s0
	global_load_lds_dwordx4 v[206:207], off
	v_lshl_add_u64 v[208:209], s[48:49], 0, v[2:3]
	s_mov_b32 m0, s50
	v_lshl_add_u64 v[210:211], s[24:25], 0, v[0:1]
	global_load_lds_dwordx4 v[208:209], off
	v_lshl_add_u64 v[208:209], s[48:49], 0, v[0:1]
	s_add_i32 m0, s50, 0x2000
	s_nop 0
	global_load_lds_dwordx4 v[208:209], off
	v_lshl_add_u64 v[208:209], s[24:25], 0, v[2:3]
	s_mov_b32 m0, s31
	s_nop 0
	global_load_lds_dwordx4 v[208:209], off
	s_mov_b32 m0, s40
	s_nop 0
	global_load_lds_dwordx4 v[210:211], off
	s_waitcnt vmcnt(8)
	s_waitcnt lgkmcnt(0)
	s_barrier
	s_setprio 1
	s_waitcnt lgkmcnt(0)
	v_mfma_f32_16x16x32_bf16 v[64:67], v[140:143], v[172:175], v[64:67]
	v_mfma_f32_16x16x32_bf16 v[64:67], v[144:147], v[176:179], v[64:67]
	v_mfma_f32_16x16x32_bf16 v[60:63], v[148:151], v[172:175], v[60:63]
	v_mfma_f32_16x16x32_bf16 v[60:63], v[152:155], v[176:179], v[60:63]
	v_mfma_f32_16x16x32_bf16 v[56:59], v[140:143], v[180:183], v[56:59]
	v_mfma_f32_16x16x32_bf16 v[56:59], v[144:147], v[184:187], v[56:59]
	v_mfma_f32_16x16x32_bf16 v[52:55], v[148:151], v[180:183], v[52:55]
	v_mfma_f32_16x16x32_bf16 v[52:55], v[152:155], v[184:187], v[52:55]
	v_mfma_f32_16x16x32_bf16 v[40:43], v[140:143], v[188:191], v[40:43]
	v_mfma_f32_16x16x32_bf16 v[40:43], v[144:147], v[192:195], v[40:43]
	v_mfma_f32_16x16x32_bf16 v[36:39], v[148:151], v[188:191], v[36:39]
	v_mfma_f32_16x16x32_bf16 v[36:39], v[152:155], v[192:195], v[36:39]
	v_mfma_f32_16x16x32_bf16 v[24:27], v[140:143], v[196:199], v[24:27]
	v_mfma_f32_16x16x32_bf16 v[24:27], v[144:147], v[200:203], v[24:27]
	v_mfma_f32_16x16x32_bf16 v[20:23], v[148:151], v[196:199], v[20:23]
	v_mfma_f32_16x16x32_bf16 v[20:23], v[152:155], v[200:203], v[20:23]
	v_mfma_f32_16x16x32_bf16 v[48:51], v[156:159], v[172:175], v[48:51]
	v_mfma_f32_16x16x32_bf16 v[48:51], v[160:163], v[176:179], v[48:51]
	v_mfma_f32_16x16x32_bf16 v[44:47], v[164:167], v[172:175], v[44:47]
	v_mfma_f32_16x16x32_bf16 v[44:47], v[168:171], v[176:179], v[44:47]
	v_mfma_f32_16x16x32_bf16 v[32:35], v[156:159], v[180:183], v[32:35]
	v_mfma_f32_16x16x32_bf16 v[32:35], v[160:163], v[184:187], v[32:35]
	v_mfma_f32_16x16x32_bf16 v[28:31], v[164:167], v[180:183], v[28:31]
	v_mfma_f32_16x16x32_bf16 v[28:31], v[168:171], v[184:187], v[28:31]
	v_mfma_f32_16x16x32_bf16 v[16:19], v[156:159], v[188:191], v[16:19]
	v_mfma_f32_16x16x32_bf16 v[16:19], v[160:163], v[192:195], v[16:19]
	v_mfma_f32_16x16x32_bf16 v[12:15], v[164:167], v[188:191], v[12:15]
	v_mfma_f32_16x16x32_bf16 v[12:15], v[168:171], v[192:195], v[12:15]
	v_mfma_f32_16x16x32_bf16 v[8:11], v[156:159], v[196:199], v[8:11]
	v_mfma_f32_16x16x32_bf16 v[8:11], v[160:163], v[200:203], v[8:11]
	v_mfma_f32_16x16x32_bf16 v[4:7], v[164:167], v[196:199], v[4:7]
	v_mfma_f32_16x16x32_bf16 v[4:7], v[168:171], v[200:203], v[4:7]
	s_setprio 0
	s_barrier
	s_sleep 2
	s_add_i32 s48, 0, 0x18000
	s_add_i32 s49, 0, 0x1c000
	v_add_u32_e32 v152, s48, v137
	v_add_u32_e32 v168, s49, v137
	ds_read_b128 v[140:143], v152
	ds_read_b128 v[144:147], v152 offset:1024
	ds_read_b128 v[148:151], v152 offset:2048
	ds_read_b128 v[152:155], v152 offset:3072
	ds_read_b128 v[156:159], v168
	ds_read_b128 v[160:163], v168 offset:1024
	ds_read_b128 v[164:167], v168 offset:2048
	ds_read_b128 v[168:171], v168 offset:3072
	s_add_u32 s24, s24, 0x80000
	s_addc_u32 s25, s25, 0
	s_mov_b32 m0, s41
	v_lshl_add_u64 v[212:213], s[24:25], 0, v[2:3]
	ds_read_b128 v[172:175], v139 offset:32768
	ds_read_b128 v[176:179], v139 offset:33792
	ds_read_b128 v[180:183], v139 offset:34816
	ds_read_b128 v[184:187], v139 offset:35840
	ds_read_b128 v[188:191], v139 offset:36864
	ds_read_b128 v[192:195], v139 offset:37888
	ds_read_b128 v[196:199], v139 offset:38912
	ds_read_b128 v[200:203], v139 offset:39936
	global_load_lds_dwordx4 v[212:213], off
	v_lshl_add_u64 v[212:213], s[24:25], 0, v[0:1]
	s_mov_b32 m0, s42
	s_nop 0
	global_load_lds_dwordx4 v[212:213], off
	s_waitcnt vmcnt(8)
	s_waitcnt lgkmcnt(0)
	s_barrier
	s_setprio 1
	s_waitcnt lgkmcnt(0)
	v_mfma_f32_16x16x32_bf16 v[128:131], v[140:143], v[172:175], v[128:131]
	v_mfma_f32_16x16x32_bf16 v[128:131], v[144:147], v[176:179], v[128:131]
	v_mfma_f32_16x16x32_bf16 v[124:127], v[148:151], v[172:175], v[124:127]
	v_mfma_f32_16x16x32_bf16 v[124:127], v[152:155], v[176:179], v[124:127]
	v_mfma_f32_16x16x32_bf16 v[120:123], v[140:143], v[180:183], v[120:123]
	v_mfma_f32_16x16x32_bf16 v[120:123], v[144:147], v[184:187], v[120:123]
	v_mfma_f32_16x16x32_bf16 v[116:119], v[148:151], v[180:183], v[116:119]
	v_mfma_f32_16x16x32_bf16 v[116:119], v[152:155], v[184:187], v[116:119]
	v_mfma_f32_16x16x32_bf16 v[108:111], v[140:143], v[188:191], v[108:111]
	v_mfma_f32_16x16x32_bf16 v[108:111], v[144:147], v[192:195], v[108:111]
	v_mfma_f32_16x16x32_bf16 v[100:103], v[148:151], v[188:191], v[100:103]
	v_mfma_f32_16x16x32_bf16 v[100:103], v[152:155], v[192:195], v[100:103]
	v_mfma_f32_16x16x32_bf16 v[92:95], v[140:143], v[196:199], v[92:95]
	v_mfma_f32_16x16x32_bf16 v[92:95], v[144:147], v[200:203], v[92:95]
	v_mfma_f32_16x16x32_bf16 v[84:87], v[148:151], v[196:199], v[84:87]
	v_mfma_f32_16x16x32_bf16 v[84:87], v[152:155], v[200:203], v[84:87]
	v_mfma_f32_16x16x32_bf16 v[112:115], v[156:159], v[172:175], v[112:115]
	v_mfma_f32_16x16x32_bf16 v[112:115], v[160:163], v[176:179], v[112:115]
	v_mfma_f32_16x16x32_bf16 v[104:107], v[164:167], v[172:175], v[104:107]
	v_mfma_f32_16x16x32_bf16 v[104:107], v[168:171], v[176:179], v[104:107]
	v_mfma_f32_16x16x32_bf16 v[96:99], v[156:159], v[180:183], v[96:99]
	v_mfma_f32_16x16x32_bf16 v[96:99], v[160:163], v[184:187], v[96:99]
	v_mfma_f32_16x16x32_bf16 v[88:91], v[164:167], v[180:183], v[88:91]
	v_mfma_f32_16x16x32_bf16 v[88:91], v[168:171], v[184:187], v[88:91]
	v_mfma_f32_16x16x32_bf16 v[80:83], v[156:159], v[188:191], v[80:83]
	v_mfma_f32_16x16x32_bf16 v[80:83], v[160:163], v[192:195], v[80:83]
	v_mfma_f32_16x16x32_bf16 v[76:79], v[164:167], v[188:191], v[76:79]
	v_mfma_f32_16x16x32_bf16 v[76:79], v[168:171], v[192:195], v[76:79]
	v_mfma_f32_16x16x32_bf16 v[72:75], v[156:159], v[196:199], v[72:75]
	v_mfma_f32_16x16x32_bf16 v[72:75], v[160:163], v[200:203], v[72:75]
	v_mfma_f32_16x16x32_bf16 v[68:71], v[164:167], v[196:199], v[68:71]
	v_mfma_f32_16x16x32_bf16 v[68:71], v[168:171], v[200:203], v[68:71]
	s_setprio 0
	s_barrier
	s_sleep 2
	s_add_i32 s24, s48, s0
	v_lshl_add_u64 v[204:205], v[204:205], 0, s[66:67]
	s_mov_b32 m0, s24
	ds_read_b128 v[172:175], v139 offset:49152
	ds_read_b128 v[176:179], v139 offset:50176
	ds_read_b128 v[180:183], v139 offset:51200
	ds_read_b128 v[184:187], v139 offset:52224
	ds_read_b128 v[188:191], v139 offset:53248
	ds_read_b128 v[192:195], v139 offset:54272
	ds_read_b128 v[196:199], v139 offset:55296
	ds_read_b128 v[200:203], v139 offset:56320
	global_load_lds_dwordx4 v[204:205], off
	s_add_i32 m0, s24, 0x2000
	s_add_u32 s22, s22, 0x80080
	v_lshl_add_u64 v[204:205], v[206:207], 0, s[66:67]
	s_addc_u32 s23, s23, 0
	s_add_i32 s24, s49, s0
	global_load_lds_dwordx4 v[204:205], off
	v_lshl_add_u64 v[204:205], s[22:23], 0, v[2:3]
	s_mov_b32 m0, s24
	s_nop 0
	global_load_lds_dwordx4 v[204:205], off
	v_lshl_add_u64 v[204:205], s[22:23], 0, v[0:1]
	s_add_i32 m0, s24, 0x2000
	s_nop 0
	global_load_lds_dwordx4 v[204:205], off
	v_lshl_add_u64 v[204:205], v[208:209], 0, s[66:67]
	s_mov_b32 m0, s1
	s_nop 0
	global_load_lds_dwordx4 v[204:205], off
	v_lshl_add_u64 v[204:205], v[210:211], 0, s[66:67]
	s_mov_b32 m0, s34
	s_nop 0
	global_load_lds_dwordx4 v[204:205], off
	s_waitcnt vmcnt(8)
	s_waitcnt lgkmcnt(0)
	s_barrier
	s_setprio 1
	s_waitcnt lgkmcnt(0)
	v_mfma_f32_16x16x32_bf16 v[64:67], v[140:143], v[172:175], v[64:67]
	v_mfma_f32_16x16x32_bf16 v[64:67], v[144:147], v[176:179], v[64:67]
	v_mfma_f32_16x16x32_bf16 v[60:63], v[148:151], v[172:175], v[60:63]
	v_mfma_f32_16x16x32_bf16 v[60:63], v[152:155], v[176:179], v[60:63]
	v_mfma_f32_16x16x32_bf16 v[56:59], v[140:143], v[180:183], v[56:59]
	v_mfma_f32_16x16x32_bf16 v[56:59], v[144:147], v[184:187], v[56:59]
	v_mfma_f32_16x16x32_bf16 v[52:55], v[148:151], v[180:183], v[52:55]
	v_mfma_f32_16x16x32_bf16 v[52:55], v[152:155], v[184:187], v[52:55]
	v_mfma_f32_16x16x32_bf16 v[40:43], v[140:143], v[188:191], v[40:43]
	v_mfma_f32_16x16x32_bf16 v[40:43], v[144:147], v[192:195], v[40:43]
	v_mfma_f32_16x16x32_bf16 v[36:39], v[148:151], v[188:191], v[36:39]
	v_mfma_f32_16x16x32_bf16 v[36:39], v[152:155], v[192:195], v[36:39]
	v_mfma_f32_16x16x32_bf16 v[24:27], v[140:143], v[196:199], v[24:27]
	v_mfma_f32_16x16x32_bf16 v[24:27], v[144:147], v[200:203], v[24:27]
	v_mfma_f32_16x16x32_bf16 v[20:23], v[148:151], v[196:199], v[20:23]
	v_mfma_f32_16x16x32_bf16 v[20:23], v[152:155], v[200:203], v[20:23]
	v_mfma_f32_16x16x32_bf16 v[48:51], v[156:159], v[172:175], v[48:51]
	v_mfma_f32_16x16x32_bf16 v[48:51], v[160:163], v[176:179], v[48:51]
	v_mfma_f32_16x16x32_bf16 v[44:47], v[164:167], v[172:175], v[44:47]
	v_mfma_f32_16x16x32_bf16 v[44:47], v[168:171], v[176:179], v[44:47]
	v_mfma_f32_16x16x32_bf16 v[32:35], v[156:159], v[180:183], v[32:35]
	v_mfma_f32_16x16x32_bf16 v[32:35], v[160:163], v[184:187], v[32:35]
	v_mfma_f32_16x16x32_bf16 v[28:31], v[164:167], v[180:183], v[28:31]
	v_mfma_f32_16x16x32_bf16 v[28:31], v[168:171], v[184:187], v[28:31]
	v_mfma_f32_16x16x32_bf16 v[16:19], v[156:159], v[188:191], v[16:19]
	v_mfma_f32_16x16x32_bf16 v[16:19], v[160:163], v[192:195], v[16:19]
	v_mfma_f32_16x16x32_bf16 v[12:15], v[164:167], v[188:191], v[12:15]
	v_mfma_f32_16x16x32_bf16 v[12:15], v[168:171], v[192:195], v[12:15]
	v_mfma_f32_16x16x32_bf16 v[8:11], v[156:159], v[196:199], v[8:11]
	v_mfma_f32_16x16x32_bf16 v[8:11], v[160:163], v[200:203], v[8:11]
	v_mfma_f32_16x16x32_bf16 v[4:7], v[164:167], v[196:199], v[4:7]
	v_mfma_f32_16x16x32_bf16 v[4:7], v[168:171], v[200:203], v[4:7]
	s_setprio 0
	s_barrier
	s_add_i32 s47, s47, 2
	s_add_u32 s20, s20, 0x100
	s_addc_u32 s21, s21, 0
	s_add_u32 s45, s45, 0x100
	s_addc_u32 s46, s46, 0
	s_cmp_gt_u32 s47, 29
	s_cbranch_scc0 .LBB0_495
	s_and_b64 vcc, exec, s[8:9]
	s_cbranch_vccz .LBB0_498
	s_barrier

.LBB0_1010:
	s_sleep 2
	s_add_u32 s24, s22, 0xfff80080
	s_addc_u32 s25, s23, -1
	s_add_i32 s49, 0, 0x10000
	s_cmp_eq_u32 s48, 28
	s_cselect_b32 s27, s13, s25
	s_cselect_b32 s26, s19, s24
	s_cselect_b32 s25, s11, s47
	s_cselect_b32 s24, s45, s46
	s_add_i32 s52, 0, 0x14000
	v_add_u32_e32 v144, s49, v219
	v_add_u32_e32 v160, s52, v219
	ds_read_b128 v[116:119], v144
	ds_read_b128 v[124:127], v144 offset:1024
	ds_read_b128 v[132:135], v144 offset:2048
	ds_read_b128 v[144:147], v144 offset:3072
	ds_read_b128 v[148:151], v160
	ds_read_b128 v[152:155], v160 offset:1024
	ds_read_b128 v[156:159], v160 offset:2048
	ds_read_b128 v[160:163], v160 offset:3072
	v_lshl_add_u64 v[204:205], s[22:23], 0, v[192:193]
	s_add_i32 m0, s21, 0xc000
	ds_read_b128 v[164:167], v221
	ds_read_b128 v[168:171], v221 offset:1024
	ds_read_b128 v[172:175], v221 offset:2048
	ds_read_b128 v[176:179], v221 offset:3072
	ds_read_b128 v[180:183], v221 offset:4096
	ds_read_b128 v[184:187], v221 offset:5120
	ds_read_b128 v[196:199], v221 offset:6144
	ds_read_b128 v[200:203], v221 offset:7168
	global_load_lds_dwordx4 v[204:205], off
	v_lshl_add_u64 v[204:205], s[22:23], 0, v[194:195]
	s_add_i32 m0, s21, 0xe000
	s_nop 0
	global_load_lds_dwordx4 v[204:205], off
	s_waitcnt vmcnt(8)
	s_waitcnt lgkmcnt(0)
	s_barrier
	s_setprio 1
	s_waitcnt lgkmcnt(0)
	v_mfma_f32_16x16x32_bf16 v[140:143], v[116:119], v[164:167], v[140:143]
	v_mfma_f32_16x16x32_bf16 v[140:143], v[124:127], v[168:171], v[140:143]
	v_mfma_f32_16x16x32_bf16 v[136:139], v[132:135], v[164:167], v[136:139]
	v_mfma_f32_16x16x32_bf16 v[136:139], v[144:147], v[168:171], v[136:139]
	v_mfma_f32_16x16x32_bf16 v[112:115], v[116:119], v[172:175], v[112:115]
	v_mfma_f32_16x16x32_bf16 v[112:115], v[124:127], v[176:179], v[112:115]
	v_mfma_f32_16x16x32_bf16 v[108:111], v[132:135], v[172:175], v[108:111]
	v_mfma_f32_16x16x32_bf16 v[108:111], v[144:147], v[176:179], v[108:111]
	v_mfma_f32_16x16x32_bf16 v[96:99], v[116:119], v[180:183], v[96:99]
	v_mfma_f32_16x16x32_bf16 v[96:99], v[124:127], v[184:187], v[96:99]
	v_mfma_f32_16x16x32_bf16 v[92:95], v[132:135], v[180:183], v[92:95]
	v_mfma_f32_16x16x32_bf16 v[92:95], v[144:147], v[184:187], v[92:95]
	v_mfma_f32_16x16x32_bf16 v[80:83], v[116:119], v[196:199], v[80:83]
	v_mfma_f32_16x16x32_bf16 v[80:83], v[124:127], v[200:203], v[80:83]
	v_mfma_f32_16x16x32_bf16 v[76:79], v[132:135], v[196:199], v[76:79]
	v_mfma_f32_16x16x32_bf16 v[76:79], v[144:147], v[200:203], v[76:79]
	v_mfma_f32_16x16x32_bf16 v[128:131], v[148:151], v[164:167], v[128:131]
	v_mfma_f32_16x16x32_bf16 v[128:131], v[152:155], v[168:171], v[128:131]
	v_mfma_f32_16x16x32_bf16 v[120:123], v[156:159], v[164:167], v[120:123]
	v_mfma_f32_16x16x32_bf16 v[120:123], v[160:163], v[168:171], v[120:123]
	v_mfma_f32_16x16x32_bf16 v[104:107], v[148:151], v[172:175], v[104:107]
	v_mfma_f32_16x16x32_bf16 v[104:107], v[152:155], v[176:179], v[104:107]
	v_mfma_f32_16x16x32_bf16 v[100:103], v[156:159], v[172:175], v[100:103]
	v_mfma_f32_16x16x32_bf16 v[100:103], v[160:163], v[176:179], v[100:103]
	v_mfma_f32_16x16x32_bf16 v[88:91], v[148:151], v[180:183], v[88:91]
	v_mfma_f32_16x16x32_bf16 v[88:91], v[152:155], v[184:187], v[88:91]
	v_mfma_f32_16x16x32_bf16 v[84:87], v[156:159], v[180:183], v[84:87]
	v_mfma_f32_16x16x32_bf16 v[84:87], v[160:163], v[184:187], v[84:87]
	v_mfma_f32_16x16x32_bf16 v[72:75], v[148:151], v[196:199], v[72:75]
	v_mfma_f32_16x16x32_bf16 v[72:75], v[152:155], v[200:203], v[72:75]
	v_mfma_f32_16x16x32_bf16 v[68:71], v[156:159], v[196:199], v[68:71]
	v_mfma_f32_16x16x32_bf16 v[68:71], v[160:163], v[200:203], v[68:71]
	s_setprio 0
	s_barrier
	s_sleep 2
	s_add_i32 s49, s49, s30
	v_lshl_add_u64 v[204:205], s[24:25], 0, v[2:3]
	s_mov_b32 m0, s49
	ds_read_b128 v[164:167], v221 offset:16384
	ds_read_b128 v[168:171], v221 offset:17408
	ds_read_b128 v[172:175], v221 offset:18432
	ds_read_b128 v[176:179], v221 offset:19456
	ds_read_b128 v[180:183], v221 offset:20480
	ds_read_b128 v[184:187], v221 offset:21504
	ds_read_b128 v[196:199], v221 offset:22528
	ds_read_b128 v[200:203], v221 offset:23552
	global_load_lds_dwordx4 v[204:205], off
	s_add_i32 m0, s49, 0x2000
	s_add_u32 s50, s24, 0x80000
	v_lshl_add_u64 v[206:207], s[24:25], 0, v[190:191]
	s_addc_u32 s51, s25, 0
	s_add_i32 s49, s52, s30
	global_load_lds_dwordx4 v[206:207], off
	v_lshl_add_u64 v[208:209], s[50:51], 0, v[2:3]
	s_mov_b32 m0, s49
	v_lshl_add_u64 v[210:211], s[26:27], 0, v[188:189]
	global_load_lds_dwordx4 v[208:209], off
	v_lshl_add_u64 v[208:209], s[50:51], 0, v[190:191]
	s_add_i32 m0, s49, 0x2000
	s_nop 0
	global_load_lds_dwordx4 v[208:209], off
	v_lshl_add_u64 v[208:209], s[26:27], 0, v[0:1]
	s_mov_b32 m0, s21
	s_nop 0
	global_load_lds_dwordx4 v[208:209], off
	s_mov_b32 m0, s31
	s_nop 0
	global_load_lds_dwordx4 v[210:211], off
	s_waitcnt vmcnt(8)
	s_waitcnt lgkmcnt(0)
	s_barrier
	s_setprio 1
	s_waitcnt lgkmcnt(0)
	v_mfma_f32_16x16x32_bf16 v[64:67], v[116:119], v[164:167], v[64:67]
	v_mfma_f32_16x16x32_bf16 v[64:67], v[124:127], v[168:171], v[64:67]
	v_mfma_f32_16x16x32_bf16 v[60:63], v[132:135], v[164:167], v[60:63]
	v_mfma_f32_16x16x32_bf16 v[60:63], v[144:147], v[168:171], v[60:63]
	v_mfma_f32_16x16x32_bf16 v[48:51], v[116:119], v[172:175], v[48:51]
	v_mfma_f32_16x16x32_bf16 v[48:51], v[124:127], v[176:179], v[48:51]
	v_mfma_f32_16x16x32_bf16 v[44:47], v[132:135], v[172:175], v[44:47]
	v_mfma_f32_16x16x32_bf16 v[44:47], v[144:147], v[176:179], v[44:47]
	v_mfma_f32_16x16x32_bf16 v[32:35], v[116:119], v[180:183], v[32:35]
	v_mfma_f32_16x16x32_bf16 v[32:35], v[124:127], v[184:187], v[32:35]
	v_mfma_f32_16x16x32_bf16 v[28:31], v[132:135], v[180:183], v[28:31]
	v_mfma_f32_16x16x32_bf16 v[28:31], v[144:147], v[184:187], v[28:31]
	v_mfma_f32_16x16x32_bf16 v[16:19], v[116:119], v[196:199], v[16:19]
	v_mfma_f32_16x16x32_bf16 v[16:19], v[124:127], v[200:203], v[16:19]
	v_mfma_f32_16x16x32_bf16 v[12:15], v[132:135], v[196:199], v[12:15]
	v_mfma_f32_16x16x32_bf16 v[12:15], v[144:147], v[200:203], v[12:15]
	v_mfma_f32_16x16x32_bf16 v[56:59], v[148:151], v[164:167], v[56:59]
	v_mfma_f32_16x16x32_bf16 v[56:59], v[152:155], v[168:171], v[56:59]
	v_mfma_f32_16x16x32_bf16 v[52:55], v[156:159], v[164:167], v[52:55]
	v_mfma_f32_16x16x32_bf16 v[52:55], v[160:163], v[168:171], v[52:55]
	v_mfma_f32_16x16x32_bf16 v[40:43], v[148:151], v[172:175], v[40:43]
	v_mfma_f32_16x16x32_bf16 v[40:43], v[152:155], v[176:179], v[40:43]
	v_mfma_f32_16x16x32_bf16 v[36:39], v[156:159], v[172:175], v[36:39]
	v_mfma_f32_16x16x32_bf16 v[36:39], v[160:163], v[176:179], v[36:39]
	v_mfma_f32_16x16x32_bf16 v[24:27], v[148:151], v[180:183], v[24:27]
	v_mfma_f32_16x16x32_bf16 v[24:27], v[152:155], v[184:187], v[24:27]
	v_mfma_f32_16x16x32_bf16 v[20:23], v[156:159], v[180:183], v[20:23]
	v_mfma_f32_16x16x32_bf16 v[20:23], v[160:163], v[184:187], v[20:23]
	v_mfma_f32_16x16x32_bf16 v[8:11], v[148:151], v[196:199], v[8:11]
	v_mfma_f32_16x16x32_bf16 v[8:11], v[152:155], v[200:203], v[8:11]
	v_mfma_f32_16x16x32_bf16 v[4:7], v[156:159], v[196:199], v[4:7]
	v_mfma_f32_16x16x32_bf16 v[4:7], v[160:163], v[200:203], v[4:7]
	s_setprio 0
	s_barrier
	s_sleep 2
	s_add_i32 s49, 0, 0x18000
	s_add_i32 s50, 0, 0x1c000
	v_add_u32_e32 v144, s49, v219
	v_add_u32_e32 v160, s50, v219
	ds_read_b128 v[116:119], v144
	ds_read_b128 v[124:127], v144 offset:1024
	ds_read_b128 v[132:135], v144 offset:2048
	ds_read_b128 v[144:147], v144 offset:3072
	ds_read_b128 v[148:151], v160
	ds_read_b128 v[152:155], v160 offset:1024
	ds_read_b128 v[156:159], v160 offset:2048
	ds_read_b128 v[160:163], v160 offset:3072
	s_add_u32 s26, s26, 0x80000
	s_addc_u32 s27, s27, 0
	s_mov_b32 m0, s35
	v_lshl_add_u64 v[212:213], s[26:27], 0, v[0:1]
	ds_read_b128 v[164:167], v221 offset:32768
	ds_read_b128 v[168:171], v221 offset:33792
	ds_read_b128 v[172:175], v221 offset:34816
	ds_read_b128 v[176:179], v221 offset:35840
	ds_read_b128 v[180:183], v221 offset:36864
	ds_read_b128 v[184:187], v221 offset:37888
	ds_read_b128 v[196:199], v221 offset:38912
	ds_read_b128 v[200:203], v221 offset:39936
	global_load_lds_dwordx4 v[212:213], off
	v_lshl_add_u64 v[212:213], s[26:27], 0, v[188:189]
	s_mov_b32 m0, s40
	s_nop 0
	global_load_lds_dwordx4 v[212:213], off
	s_waitcnt vmcnt(8)
	s_waitcnt lgkmcnt(0)
	s_barrier
	s_setprio 1
	s_waitcnt lgkmcnt(0)
	v_mfma_f32_16x16x32_bf16 v[140:143], v[116:119], v[164:167], v[140:143]
	v_mfma_f32_16x16x32_bf16 v[140:143], v[124:127], v[168:171], v[140:143]
	v_mfma_f32_16x16x32_bf16 v[136:139], v[132:135], v[164:167], v[136:139]
	v_mfma_f32_16x16x32_bf16 v[136:139], v[144:147], v[168:171], v[136:139]
	v_mfma_f32_16x16x32_bf16 v[112:115], v[116:119], v[172:175], v[112:115]
	v_mfma_f32_16x16x32_bf16 v[112:115], v[124:127], v[176:179], v[112:115]
	v_mfma_f32_16x16x32_bf16 v[108:111], v[132:135], v[172:175], v[108:111]
	v_mfma_f32_16x16x32_bf16 v[108:111], v[144:147], v[176:179], v[108:111]
	v_mfma_f32_16x16x32_bf16 v[96:99], v[116:119], v[180:183], v[96:99]
	v_mfma_f32_16x16x32_bf16 v[96:99], v[124:127], v[184:187], v[96:99]
	v_mfma_f32_16x16x32_bf16 v[92:95], v[132:135], v[180:183], v[92:95]
	v_mfma_f32_16x16x32_bf16 v[92:95], v[144:147], v[184:187], v[92:95]
	v_mfma_f32_16x16x32_bf16 v[80:83], v[116:119], v[196:199], v[80:83]
	v_mfma_f32_16x16x32_bf16 v[80:83], v[124:127], v[200:203], v[80:83]
	v_mfma_f32_16x16x32_bf16 v[76:79], v[132:135], v[196:199], v[76:79]
	v_mfma_f32_16x16x32_bf16 v[76:79], v[144:147], v[200:203], v[76:79]
	v_mfma_f32_16x16x32_bf16 v[128:131], v[148:151], v[164:167], v[128:131]
	v_mfma_f32_16x16x32_bf16 v[128:131], v[152:155], v[168:171], v[128:131]
	v_mfma_f32_16x16x32_bf16 v[120:123], v[156:159], v[164:167], v[120:123]
	v_mfma_f32_16x16x32_bf16 v[120:123], v[160:163], v[168:171], v[120:123]
	v_mfma_f32_16x16x32_bf16 v[104:107], v[148:151], v[172:175], v[104:107]
	v_mfma_f32_16x16x32_bf16 v[104:107], v[152:155], v[176:179], v[104:107]
	v_mfma_f32_16x16x32_bf16 v[100:103], v[156:159], v[172:175], v[100:103]
	v_mfma_f32_16x16x32_bf16 v[100:103], v[160:163], v[176:179], v[100:103]
	v_mfma_f32_16x16x32_bf16 v[88:91], v[148:151], v[180:183], v[88:91]
	v_mfma_f32_16x16x32_bf16 v[88:91], v[152:155], v[184:187], v[88:91]
	v_mfma_f32_16x16x32_bf16 v[84:87], v[156:159], v[180:183], v[84:87]
	v_mfma_f32_16x16x32_bf16 v[84:87], v[160:163], v[184:187], v[84:87]
	v_mfma_f32_16x16x32_bf16 v[72:75], v[148:151], v[196:199], v[72:75]
	v_mfma_f32_16x16x32_bf16 v[72:75], v[152:155], v[200:203], v[72:75]
	v_mfma_f32_16x16x32_bf16 v[68:71], v[156:159], v[196:199], v[68:71]
	v_mfma_f32_16x16x32_bf16 v[68:71], v[160:163], v[200:203], v[68:71]
	s_setprio 0
	s_barrier
	s_sleep 2
	s_add_i32 s26, s49, s30
	v_lshl_add_u64 v[204:205], v[204:205], 0, s[66:67]
	s_mov_b32 m0, s26
	ds_read_b128 v[164:167], v221 offset:49152
	ds_read_b128 v[168:171], v221 offset:50176
	ds_read_b128 v[172:175], v221 offset:51200
	ds_read_b128 v[176:179], v221 offset:52224
	ds_read_b128 v[180:183], v221 offset:53248
	ds_read_b128 v[184:187], v221 offset:54272
	ds_read_b128 v[196:199], v221 offset:55296
	ds_read_b128 v[200:203], v221 offset:56320
	global_load_lds_dwordx4 v[204:205], off
	s_add_i32 m0, s26, 0x2000
	s_add_u32 s24, s24, 0x80080
	v_lshl_add_u64 v[204:205], v[206:207], 0, s[66:67]
	s_addc_u32 s25, s25, 0
	s_add_i32 s26, s50, s30
	global_load_lds_dwordx4 v[204:205], off
	v_lshl_add_u64 v[204:205], s[24:25], 0, v[2:3]
	s_mov_b32 m0, s26
	s_nop 0
	global_load_lds_dwordx4 v[204:205], off
	v_lshl_add_u64 v[204:205], s[24:25], 0, v[190:191]
	s_add_i32 m0, s26, 0x2000
	s_nop 0
	global_load_lds_dwordx4 v[204:205], off
	v_lshl_add_u64 v[204:205], v[208:209], 0, s[66:67]
	s_mov_b32 m0, s41
	s_nop 0
	global_load_lds_dwordx4 v[204:205], off
	v_lshl_add_u64 v[204:205], v[210:211], 0, s[66:67]
	s_mov_b32 m0, s42
	s_nop 0
	global_load_lds_dwordx4 v[204:205], off
	s_waitcnt vmcnt(8)
	s_waitcnt lgkmcnt(0)
	s_barrier
	s_setprio 1
	s_waitcnt lgkmcnt(0)
	v_mfma_f32_16x16x32_bf16 v[64:67], v[116:119], v[164:167], v[64:67]
	v_mfma_f32_16x16x32_bf16 v[64:67], v[124:127], v[168:171], v[64:67]
	v_mfma_f32_16x16x32_bf16 v[60:63], v[132:135], v[164:167], v[60:63]
	v_mfma_f32_16x16x32_bf16 v[60:63], v[144:147], v[168:171], v[60:63]
	v_mfma_f32_16x16x32_bf16 v[48:51], v[116:119], v[172:175], v[48:51]
	v_mfma_f32_16x16x32_bf16 v[48:51], v[124:127], v[176:179], v[48:51]
	v_mfma_f32_16x16x32_bf16 v[44:47], v[132:135], v[172:175], v[44:47]
	v_mfma_f32_16x16x32_bf16 v[44:47], v[144:147], v[176:179], v[44:47]
	v_mfma_f32_16x16x32_bf16 v[32:35], v[116:119], v[180:183], v[32:35]
	v_mfma_f32_16x16x32_bf16 v[32:35], v[124:127], v[184:187], v[32:35]
	v_mfma_f32_16x16x32_bf16 v[28:31], v[132:135], v[180:183], v[28:31]
	v_mfma_f32_16x16x32_bf16 v[28:31], v[144:147], v[184:187], v[28:31]
	v_mfma_f32_16x16x32_bf16 v[16:19], v[116:119], v[196:199], v[16:19]
	v_mfma_f32_16x16x32_bf16 v[16:19], v[124:127], v[200:203], v[16:19]
	v_mfma_f32_16x16x32_bf16 v[12:15], v[132:135], v[196:199], v[12:15]
	v_mfma_f32_16x16x32_bf16 v[12:15], v[144:147], v[200:203], v[12:15]
	v_mfma_f32_16x16x32_bf16 v[56:59], v[148:151], v[164:167], v[56:59]
	v_mfma_f32_16x16x32_bf16 v[56:59], v[152:155], v[168:171], v[56:59]
	v_mfma_f32_16x16x32_bf16 v[52:55], v[156:159], v[164:167], v[52:55]
	v_mfma_f32_16x16x32_bf16 v[52:55], v[160:163], v[168:171], v[52:55]
	v_mfma_f32_16x16x32_bf16 v[40:43], v[148:151], v[172:175], v[40:43]
	v_mfma_f32_16x16x32_bf16 v[40:43], v[152:155], v[176:179], v[40:43]
	v_mfma_f32_16x16x32_bf16 v[36:39], v[156:159], v[172:175], v[36:39]
	v_mfma_f32_16x16x32_bf16 v[36:39], v[160:163], v[176:179], v[36:39]
	v_mfma_f32_16x16x32_bf16 v[24:27], v[148:151], v[180:183], v[24:27]
	v_mfma_f32_16x16x32_bf16 v[24:27], v[152:155], v[184:187], v[24:27]
	v_mfma_f32_16x16x32_bf16 v[20:23], v[156:159], v[180:183], v[20:23]
	v_mfma_f32_16x16x32_bf16 v[20:23], v[160:163], v[184:187], v[20:23]
	v_mfma_f32_16x16x32_bf16 v[8:11], v[148:151], v[196:199], v[8:11]
	v_mfma_f32_16x16x32_bf16 v[8:11], v[152:155], v[200:203], v[8:11]
	v_mfma_f32_16x16x32_bf16 v[4:7], v[156:159], v[196:199], v[4:7]
	v_mfma_f32_16x16x32_bf16 v[4:7], v[160:163], v[200:203], v[4:7]
	s_setprio 0
	s_barrier
	s_add_i32 s48, s48, 2
	s_add_u32 s22, s22, 0x100
	s_addc_u32 s23, s23, 0
	s_add_u32 s46, s46, 0x100
	s_addc_u32 s47, s47, 0
	s_cmp_gt_u32 s48, 29
	s_cbranch_scc0 .LBB0_1010
	s_and_b64 vcc, exec, s[8:9]
	s_cbranch_vccz .LBB0_1013
	s_barrier
